# code placement: 19 s_nop 0 inserted before segment barriers so every v_mfma 16x16x32 block in the GEMM loops starts 8-byte aligned (v087 otherwise)
# baseline (speedup 1.0000x reference)
.LBB0_538:
	ds_read_b128 v[152:155], v149
	ds_read_b128 v[156:159], v149 offset:1024
	ds_read_b128 v[160:163], v149 offset:2048
	ds_read_b128 v[164:167], v149 offset:3072
	ds_read_b128 v[168:171], v150
	ds_read_b128 v[172:175], v150 offset:1024
	ds_read_b128 v[176:179], v150 offset:2048
	ds_read_b128 v[180:183], v150 offset:3072
	s_add_u32 s40, s38, 0xfffc0080
	s_addc_u32 s41, s39, -1
	s_cmp_eq_u32 s54, 12
	s_cselect_b32 s43, s27, s41
	s_cselect_b32 s42, s50, s40
	s_cselect_b32 s41, s25, s53
	s_cselect_b32 s40, s51, s52
	s_add_i32 m0, s11, 0xc000
	ds_read_b128 v[184:187], v151
	ds_read_b128 v[188:191], v151 offset:1024
	ds_read_b128 v[192:195], v151 offset:2048
	ds_read_b128 v[196:199], v151 offset:3072
	ds_read_b128 v[200:203], v151 offset:4096
	ds_read_b128 v[204:207], v151 offset:5120
	ds_read_b128 v[212:215], v151 offset:6144
	ds_read_b128 v[216:219], v151 offset:7168
	global_load_lds_dwordx4 v136, s[38:39]
	s_add_i32 m0, s11, 0xe000
	s_nop 0
	global_load_lds_dwordx4 v138, s[38:39]
	s_waitcnt vmcnt(8)
	s_waitcnt lgkmcnt(0)
	s_barrier
	s_setprio 1
	s_waitcnt lgkmcnt(0)
	v_mfma_f32_16x16x32_bf16 v[124:127], v[152:155], v[184:187], v[124:127]
	v_mfma_f32_16x16x32_bf16 v[120:123], v[160:163], v[184:187], v[120:123]
	v_mfma_f32_16x16x32_bf16 v[108:111], v[152:155], v[192:195], v[108:111]
	v_mfma_f32_16x16x32_bf16 v[104:107], v[160:163], v[192:195], v[104:107]
	v_mfma_f32_16x16x32_bf16 v[92:95], v[152:155], v[200:203], v[92:95]
	v_mfma_f32_16x16x32_bf16 v[88:91], v[160:163], v[200:203], v[88:91]
	v_mfma_f32_16x16x32_bf16 v[76:79], v[152:155], v[212:215], v[76:79]
	v_mfma_f32_16x16x32_bf16 v[72:75], v[160:163], v[212:215], v[72:75]
	v_mfma_f32_16x16x32_bf16 v[124:127], v[156:159], v[188:191], v[124:127]
	v_mfma_f32_16x16x32_bf16 v[120:123], v[164:167], v[188:191], v[120:123]
	v_mfma_f32_16x16x32_bf16 v[108:111], v[156:159], v[196:199], v[108:111]
	v_mfma_f32_16x16x32_bf16 v[104:107], v[164:167], v[196:199], v[104:107]
	v_mfma_f32_16x16x32_bf16 v[92:95], v[156:159], v[204:207], v[92:95]
	v_mfma_f32_16x16x32_bf16 v[88:91], v[164:167], v[204:207], v[88:91]
	v_mfma_f32_16x16x32_bf16 v[76:79], v[156:159], v[216:219], v[76:79]
	v_mfma_f32_16x16x32_bf16 v[72:75], v[164:167], v[216:219], v[72:75]
	s_setprio 0
	s_setprio 1
	v_mfma_f32_16x16x32_bf16 v[116:119], v[168:171], v[184:187], v[116:119]
	v_mfma_f32_16x16x32_bf16 v[112:115], v[176:179], v[184:187], v[112:115]
	v_mfma_f32_16x16x32_bf16 v[100:103], v[168:171], v[192:195], v[100:103]
	v_mfma_f32_16x16x32_bf16 v[96:99], v[176:179], v[192:195], v[96:99]
	v_mfma_f32_16x16x32_bf16 v[84:87], v[168:171], v[200:203], v[84:87]
	v_mfma_f32_16x16x32_bf16 v[80:83], v[176:179], v[200:203], v[80:83]
	v_mfma_f32_16x16x32_bf16 v[68:71], v[168:171], v[212:215], v[68:71]
	v_mfma_f32_16x16x32_bf16 v[64:67], v[176:179], v[212:215], v[64:67]
	v_mfma_f32_16x16x32_bf16 v[116:119], v[172:175], v[188:191], v[116:119]
	v_mfma_f32_16x16x32_bf16 v[112:115], v[180:183], v[188:191], v[112:115]
	v_mfma_f32_16x16x32_bf16 v[100:103], v[172:175], v[196:199], v[100:103]
	v_mfma_f32_16x16x32_bf16 v[96:99], v[180:183], v[196:199], v[96:99]
	v_mfma_f32_16x16x32_bf16 v[84:87], v[172:175], v[204:207], v[84:87]
	v_mfma_f32_16x16x32_bf16 v[80:83], v[180:183], v[204:207], v[80:83]
	v_mfma_f32_16x16x32_bf16 v[68:71], v[172:175], v[216:219], v[68:71]
	v_mfma_f32_16x16x32_bf16 v[64:67], v[180:183], v[216:219], v[64:67]
	s_setprio 0
	s_barrier
	s_add_i32 s55, s45, s10
	v_lshl_add_u64 v[144:145], s[40:41], 0, v[132:133]
	s_mov_b32 m0, s55
	ds_read_b128 v[184:187], v151 offset:16384
	ds_read_b128 v[188:191], v151 offset:17408
	ds_read_b128 v[192:195], v151 offset:18432
	ds_read_b128 v[196:199], v151 offset:19456
	ds_read_b128 v[200:203], v151 offset:20480
	ds_read_b128 v[204:207], v151 offset:21504
	ds_read_b128 v[212:215], v151 offset:22528
	ds_read_b128 v[216:219], v151 offset:23552
	global_load_lds_dwordx4 v[144:145], off
	s_add_i32 m0, s55, 0x2000
	s_add_u32 s56, s40, 0x40000
	v_lshl_add_u64 v[208:209], s[40:41], 0, v[128:129]
	s_addc_u32 s57, s41, 0
	s_add_i32 s55, s46, s10
	global_load_lds_dwordx4 v[208:209], off
	s_mov_b32 m0, s55
	v_lshl_add_u64 v[222:223], s[42:43], 0, v[130:131]
	global_load_lds_dwordx4 v132, s[56:57]
	s_add_i32 m0, s55, 0x2000
	s_nop 0
	global_load_lds_dwordx4 v128, s[56:57]
	v_lshl_add_u64 v[220:221], s[42:43], 0, v[134:135]
	s_mov_b32 m0, s11
	s_nop 0
	global_load_lds_dwordx4 v[220:221], off
	s_mov_b32 m0, s14
	s_nop 0
	global_load_lds_dwordx4 v[222:223], off
	s_waitcnt vmcnt(8)
	s_waitcnt lgkmcnt(0)
	s_nop 0
	s_barrier
	s_setprio 1
	s_waitcnt lgkmcnt(0)
	v_mfma_f32_16x16x32_bf16 v[60:63], v[152:155], v[184:187], v[60:63]
	v_mfma_f32_16x16x32_bf16 v[56:59], v[160:163], v[184:187], v[56:59]
	v_mfma_f32_16x16x32_bf16 v[44:47], v[152:155], v[192:195], v[44:47]
	v_mfma_f32_16x16x32_bf16 v[40:43], v[160:163], v[192:195], v[40:43]
	v_mfma_f32_16x16x32_bf16 v[28:31], v[152:155], v[200:203], v[28:31]
	v_mfma_f32_16x16x32_bf16 v[24:27], v[160:163], v[200:203], v[24:27]
	v_mfma_f32_16x16x32_bf16 v[12:15], v[152:155], v[212:215], v[12:15]
	v_mfma_f32_16x16x32_bf16 v[8:11], v[160:163], v[212:215], v[8:11]
	v_mfma_f32_16x16x32_bf16 v[60:63], v[156:159], v[188:191], v[60:63]
	v_mfma_f32_16x16x32_bf16 v[56:59], v[164:167], v[188:191], v[56:59]
	v_mfma_f32_16x16x32_bf16 v[44:47], v[156:159], v[196:199], v[44:47]
	v_mfma_f32_16x16x32_bf16 v[40:43], v[164:167], v[196:199], v[40:43]
	v_mfma_f32_16x16x32_bf16 v[28:31], v[156:159], v[204:207], v[28:31]
	v_mfma_f32_16x16x32_bf16 v[24:27], v[164:167], v[204:207], v[24:27]
	v_mfma_f32_16x16x32_bf16 v[12:15], v[156:159], v[216:219], v[12:15]
	v_mfma_f32_16x16x32_bf16 v[8:11], v[164:167], v[216:219], v[8:11]
	s_setprio 0
	s_setprio 1
	v_mfma_f32_16x16x32_bf16 v[52:55], v[168:171], v[184:187], v[52:55]
	v_mfma_f32_16x16x32_bf16 v[48:51], v[176:179], v[184:187], v[48:51]
	v_mfma_f32_16x16x32_bf16 v[36:39], v[168:171], v[192:195], v[36:39]
	v_mfma_f32_16x16x32_bf16 v[32:35], v[176:179], v[192:195], v[32:35]
	v_mfma_f32_16x16x32_bf16 v[20:23], v[168:171], v[200:203], v[20:23]
	v_mfma_f32_16x16x32_bf16 v[16:19], v[176:179], v[200:203], v[16:19]
	v_mfma_f32_16x16x32_bf16 v[4:7], v[168:171], v[212:215], v[4:7]
	v_mfma_f32_16x16x32_bf16 v[0:3], v[176:179], v[212:215], v[0:3]
	v_mfma_f32_16x16x32_bf16 v[52:55], v[172:175], v[188:191], v[52:55]
	v_mfma_f32_16x16x32_bf16 v[48:51], v[180:183], v[188:191], v[48:51]
	v_mfma_f32_16x16x32_bf16 v[36:39], v[172:175], v[196:199], v[36:39]
	v_mfma_f32_16x16x32_bf16 v[32:35], v[180:183], v[196:199], v[32:35]
	v_mfma_f32_16x16x32_bf16 v[20:23], v[172:175], v[204:207], v[20:23]
	v_mfma_f32_16x16x32_bf16 v[16:19], v[180:183], v[204:207], v[16:19]
	v_mfma_f32_16x16x32_bf16 v[4:7], v[172:175], v[216:219], v[4:7]
	v_mfma_f32_16x16x32_bf16 v[0:3], v[180:183], v[216:219], v[0:3]
	s_setprio 0
	s_barrier
	s_add_i32 s55, 0, 0x18000
	s_add_i32 s56, 0, 0x1c000
	v_add_u32_e32 v164, s55, v147
	v_add_u32_e32 v180, s56, v147
	ds_read_b128 v[152:155], v164
	ds_read_b128 v[156:159], v164 offset:1024
	ds_read_b128 v[160:163], v164 offset:2048
	ds_read_b128 v[164:167], v164 offset:3072
	ds_read_b128 v[168:171], v180
	ds_read_b128 v[172:175], v180 offset:1024
	ds_read_b128 v[176:179], v180 offset:2048
	ds_read_b128 v[180:183], v180 offset:3072
	s_add_u32 s42, s42, 0x40000
	s_addc_u32 s43, s43, 0
	s_mov_b32 m0, s15
	ds_read_b128 v[184:187], v151 offset:32768
	ds_read_b128 v[188:191], v151 offset:33792
	ds_read_b128 v[192:195], v151 offset:34816
	ds_read_b128 v[196:199], v151 offset:35840
	ds_read_b128 v[200:203], v151 offset:36864
	ds_read_b128 v[204:207], v151 offset:37888
	ds_read_b128 v[212:215], v151 offset:38912
	ds_read_b128 v[216:219], v151 offset:39936
	global_load_lds_dwordx4 v134, s[42:43]
	s_mov_b32 m0, s28
	s_nop 0
	global_load_lds_dwordx4 v130, s[42:43]
	s_waitcnt vmcnt(8)
	s_waitcnt lgkmcnt(0)
	s_nop 0
	s_barrier
	s_setprio 1
	s_waitcnt lgkmcnt(0)
	v_mfma_f32_16x16x32_bf16 v[124:127], v[152:155], v[184:187], v[124:127]
	v_mfma_f32_16x16x32_bf16 v[120:123], v[160:163], v[184:187], v[120:123]
	v_mfma_f32_16x16x32_bf16 v[108:111], v[152:155], v[192:195], v[108:111]
	v_mfma_f32_16x16x32_bf16 v[104:107], v[160:163], v[192:195], v[104:107]
	v_mfma_f32_16x16x32_bf16 v[92:95], v[152:155], v[200:203], v[92:95]
	v_mfma_f32_16x16x32_bf16 v[88:91], v[160:163], v[200:203], v[88:91]
	v_mfma_f32_16x16x32_bf16 v[76:79], v[152:155], v[212:215], v[76:79]
	v_mfma_f32_16x16x32_bf16 v[72:75], v[160:163], v[212:215], v[72:75]
	v_mfma_f32_16x16x32_bf16 v[124:127], v[156:159], v[188:191], v[124:127]
	v_mfma_f32_16x16x32_bf16 v[120:123], v[164:167], v[188:191], v[120:123]
	v_mfma_f32_16x16x32_bf16 v[108:111], v[156:159], v[196:199], v[108:111]
	v_mfma_f32_16x16x32_bf16 v[104:107], v[164:167], v[196:199], v[104:107]
	v_mfma_f32_16x16x32_bf16 v[92:95], v[156:159], v[204:207], v[92:95]
	v_mfma_f32_16x16x32_bf16 v[88:91], v[164:167], v[204:207], v[88:91]
	v_mfma_f32_16x16x32_bf16 v[76:79], v[156:159], v[216:219], v[76:79]
	v_mfma_f32_16x16x32_bf16 v[72:75], v[164:167], v[216:219], v[72:75]
	s_setprio 0
	s_setprio 1
	v_mfma_f32_16x16x32_bf16 v[116:119], v[168:171], v[184:187], v[116:119]
	v_mfma_f32_16x16x32_bf16 v[112:115], v[176:179], v[184:187], v[112:115]
	v_mfma_f32_16x16x32_bf16 v[100:103], v[168:171], v[192:195], v[100:103]
	v_mfma_f32_16x16x32_bf16 v[96:99], v[176:179], v[192:195], v[96:99]
	v_mfma_f32_16x16x32_bf16 v[84:87], v[168:171], v[200:203], v[84:87]
	v_mfma_f32_16x16x32_bf16 v[80:83], v[176:179], v[200:203], v[80:83]
	v_mfma_f32_16x16x32_bf16 v[68:71], v[168:171], v[212:215], v[68:71]
	v_mfma_f32_16x16x32_bf16 v[64:67], v[176:179], v[212:215], v[64:67]
	v_mfma_f32_16x16x32_bf16 v[116:119], v[172:175], v[188:191], v[116:119]
	v_mfma_f32_16x16x32_bf16 v[112:115], v[180:183], v[188:191], v[112:115]
	v_mfma_f32_16x16x32_bf16 v[100:103], v[172:175], v[196:199], v[100:103]
	v_mfma_f32_16x16x32_bf16 v[96:99], v[180:183], v[196:199], v[96:99]
	v_mfma_f32_16x16x32_bf16 v[84:87], v[172:175], v[204:207], v[84:87]
	v_mfma_f32_16x16x32_bf16 v[80:83], v[180:183], v[204:207], v[80:83]
	v_mfma_f32_16x16x32_bf16 v[68:71], v[172:175], v[216:219], v[68:71]
	v_mfma_f32_16x16x32_bf16 v[64:67], v[180:183], v[216:219], v[64:67]
	s_setprio 0
	s_barrier
	s_add_i32 s42, s55, s10
	v_lshl_add_u64 v[144:145], v[144:145], 0, s[4:5]
	s_mov_b32 m0, s42
	ds_read_b128 v[184:187], v151 offset:49152
	ds_read_b128 v[188:191], v151 offset:50176
	ds_read_b128 v[192:195], v151 offset:51200
	ds_read_b128 v[196:199], v151 offset:52224
	ds_read_b128 v[200:203], v151 offset:53248
	ds_read_b128 v[204:207], v151 offset:54272
	ds_read_b128 v[212:215], v151 offset:55296
	ds_read_b128 v[216:219], v151 offset:56320
	global_load_lds_dwordx4 v[144:145], off
	s_add_i32 m0, s42, 0x2000
	s_add_u32 s40, s40, 0x40080
	v_lshl_add_u64 v[144:145], v[208:209], 0, s[4:5]
	s_addc_u32 s41, s41, 0
	s_add_i32 s42, s56, s10
	global_load_lds_dwordx4 v[144:145], off
	s_mov_b32 m0, s42
	s_nop 0
	global_load_lds_dwordx4 v132, s[40:41]
	s_add_i32 m0, s42, 0x2000
	s_nop 0
	global_load_lds_dwordx4 v128, s[40:41]
	v_lshl_add_u64 v[144:145], v[220:221], 0, s[4:5]
	s_mov_b32 m0, s29
	s_nop 0
	global_load_lds_dwordx4 v[144:145], off
	v_lshl_add_u64 v[144:145], v[222:223], 0, s[4:5]
	s_mov_b32 m0, s33
	s_nop 0
	global_load_lds_dwordx4 v[144:145], off
	s_waitcnt vmcnt(8)
	s_waitcnt lgkmcnt(0)
	s_barrier
	s_setprio 1
	s_waitcnt lgkmcnt(0)
	v_mfma_f32_16x16x32_bf16 v[60:63], v[152:155], v[184:187], v[60:63]
	v_mfma_f32_16x16x32_bf16 v[56:59], v[160:163], v[184:187], v[56:59]
	v_mfma_f32_16x16x32_bf16 v[44:47], v[152:155], v[192:195], v[44:47]
	v_mfma_f32_16x16x32_bf16 v[40:43], v[160:163], v[192:195], v[40:43]
	v_mfma_f32_16x16x32_bf16 v[28:31], v[152:155], v[200:203], v[28:31]
	v_mfma_f32_16x16x32_bf16 v[24:27], v[160:163], v[200:203], v[24:27]
	v_mfma_f32_16x16x32_bf16 v[12:15], v[152:155], v[212:215], v[12:15]
	v_mfma_f32_16x16x32_bf16 v[8:11], v[160:163], v[212:215], v[8:11]
	v_mfma_f32_16x16x32_bf16 v[60:63], v[156:159], v[188:191], v[60:63]
	v_mfma_f32_16x16x32_bf16 v[56:59], v[164:167], v[188:191], v[56:59]
	v_mfma_f32_16x16x32_bf16 v[44:47], v[156:159], v[196:199], v[44:47]
	v_mfma_f32_16x16x32_bf16 v[40:43], v[164:167], v[196:199], v[40:43]
	v_mfma_f32_16x16x32_bf16 v[28:31], v[156:159], v[204:207], v[28:31]
	v_mfma_f32_16x16x32_bf16 v[24:27], v[164:167], v[204:207], v[24:27]
	v_mfma_f32_16x16x32_bf16 v[12:15], v[156:159], v[216:219], v[12:15]
	v_mfma_f32_16x16x32_bf16 v[8:11], v[164:167], v[216:219], v[8:11]
	s_setprio 0
	s_setprio 1
	v_mfma_f32_16x16x32_bf16 v[52:55], v[168:171], v[184:187], v[52:55]
	v_mfma_f32_16x16x32_bf16 v[48:51], v[176:179], v[184:187], v[48:51]
	v_mfma_f32_16x16x32_bf16 v[36:39], v[168:171], v[192:195], v[36:39]
	v_mfma_f32_16x16x32_bf16 v[32:35], v[176:179], v[192:195], v[32:35]
	v_mfma_f32_16x16x32_bf16 v[20:23], v[168:171], v[200:203], v[20:23]
	v_mfma_f32_16x16x32_bf16 v[16:19], v[176:179], v[200:203], v[16:19]
	v_mfma_f32_16x16x32_bf16 v[4:7], v[168:171], v[212:215], v[4:7]
	v_mfma_f32_16x16x32_bf16 v[0:3], v[176:179], v[212:215], v[0:3]
	v_mfma_f32_16x16x32_bf16 v[52:55], v[172:175], v[188:191], v[52:55]
	v_mfma_f32_16x16x32_bf16 v[48:51], v[180:183], v[188:191], v[48:51]
	v_mfma_f32_16x16x32_bf16 v[36:39], v[172:175], v[196:199], v[36:39]
	v_mfma_f32_16x16x32_bf16 v[32:35], v[180:183], v[196:199], v[32:35]
	v_mfma_f32_16x16x32_bf16 v[20:23], v[172:175], v[204:207], v[20:23]
	v_mfma_f32_16x16x32_bf16 v[16:19], v[180:183], v[204:207], v[16:19]
	v_mfma_f32_16x16x32_bf16 v[4:7], v[172:175], v[216:219], v[4:7]
	v_mfma_f32_16x16x32_bf16 v[0:3], v[180:183], v[216:219], v[0:3]
	s_setprio 0
	s_barrier
	s_add_i32 s54, s54, 2
	s_add_u32 s38, s38, 0x100
	s_addc_u32 s39, s39, 0
	s_add_u32 s52, s52, 0x100
	s_addc_u32 s53, s53, 0
	s_cmp_gt_u32 s54, 13
	s_cbranch_scc0 .LBB0_538
	s_and_b64 vcc, exec, s[8:9]
	s_cbranch_vccz .LBB0_541
	s_barrier

.LBB0_617:
	ds_read_b128 v[32:35], v186
	ds_read_b128 v[36:39], v186 offset:1024
	ds_read_b128 v[40:43], v186 offset:2048
	ds_read_b128 v[44:47], v186 offset:3072
	ds_read_b128 v[48:51], v187
	ds_read_b128 v[52:55], v187 offset:1024
	ds_read_b128 v[56:59], v187 offset:2048
	ds_read_b128 v[60:63], v187 offset:3072
	s_add_u32 s38, s2, 0x100
	s_addc_u32 s39, s3, 0
	s_cmp_eq_u32 s52, 40
	s_cselect_b32 s43, s7, s39
	s_cselect_b32 s42, s6, s38
	s_cselect_b32 s41, s37, s51
	s_cselect_b32 s40, s36, s1
	s_add_i32 m0, s11, 0xc000
	ds_read_b128 v[176:179], v188
	ds_read_b128 v[190:193], v188 offset:1024
	ds_read_b128 v[194:197], v188 offset:2048
	ds_read_b128 v[198:201], v188 offset:3072
	ds_read_b128 v[202:205], v188 offset:4096
	ds_read_b128 v[206:209], v188 offset:5120
	ds_read_b128 v[212:215], v188 offset:6144
	ds_read_b128 v[216:219], v188 offset:7168
	global_load_lds_dwordx4 v168, s[2:3]
	s_add_i32 m0, s11, 0xe000
	s_nop 0
	global_load_lds_dwordx4 v170, s[2:3]
	s_waitcnt vmcnt(8)
	s_waitcnt lgkmcnt(0)
	s_barrier
	s_setprio 1
	s_waitcnt lgkmcnt(0)
	v_mfma_f32_16x16x32_bf16 v[156:159], v[32:35], v[176:179], v[156:159]
	v_mfma_f32_16x16x32_bf16 v[152:155], v[40:43], v[176:179], v[152:155]
	v_mfma_f32_16x16x32_bf16 v[140:143], v[32:35], v[194:197], v[140:143]
	v_mfma_f32_16x16x32_bf16 v[136:139], v[40:43], v[194:197], v[136:139]
	v_mfma_f32_16x16x32_bf16 v[124:127], v[32:35], v[202:205], v[124:127]
	v_mfma_f32_16x16x32_bf16 v[120:123], v[40:43], v[202:205], v[120:123]
	v_mfma_f32_16x16x32_bf16 v[108:111], v[32:35], v[212:215], v[108:111]
	v_mfma_f32_16x16x32_bf16 v[104:107], v[40:43], v[212:215], v[104:107]
	v_mfma_f32_16x16x32_bf16 v[156:159], v[36:39], v[190:193], v[156:159]
	v_mfma_f32_16x16x32_bf16 v[152:155], v[44:47], v[190:193], v[152:155]
	v_mfma_f32_16x16x32_bf16 v[140:143], v[36:39], v[198:201], v[140:143]
	v_mfma_f32_16x16x32_bf16 v[136:139], v[44:47], v[198:201], v[136:139]
	v_mfma_f32_16x16x32_bf16 v[124:127], v[36:39], v[206:209], v[124:127]
	v_mfma_f32_16x16x32_bf16 v[120:123], v[44:47], v[206:209], v[120:123]
	v_mfma_f32_16x16x32_bf16 v[108:111], v[36:39], v[216:219], v[108:111]
	v_mfma_f32_16x16x32_bf16 v[104:107], v[44:47], v[216:219], v[104:107]
	s_setprio 0
	s_setprio 1
	v_mfma_f32_16x16x32_bf16 v[148:151], v[48:51], v[176:179], v[148:151]
	v_mfma_f32_16x16x32_bf16 v[144:147], v[56:59], v[176:179], v[144:147]
	v_mfma_f32_16x16x32_bf16 v[132:135], v[48:51], v[194:197], v[132:135]
	v_mfma_f32_16x16x32_bf16 v[128:131], v[56:59], v[194:197], v[128:131]
	v_mfma_f32_16x16x32_bf16 v[116:119], v[48:51], v[202:205], v[116:119]
	v_mfma_f32_16x16x32_bf16 v[112:115], v[56:59], v[202:205], v[112:115]
	v_mfma_f32_16x16x32_bf16 v[100:103], v[48:51], v[212:215], v[100:103]
	v_mfma_f32_16x16x32_bf16 v[96:99], v[56:59], v[212:215], v[96:99]
	v_mfma_f32_16x16x32_bf16 v[148:151], v[52:55], v[190:193], v[148:151]
	v_mfma_f32_16x16x32_bf16 v[144:147], v[60:63], v[190:193], v[144:147]
	v_mfma_f32_16x16x32_bf16 v[132:135], v[52:55], v[198:201], v[132:135]
	v_mfma_f32_16x16x32_bf16 v[128:131], v[60:63], v[198:201], v[128:131]
	v_mfma_f32_16x16x32_bf16 v[116:119], v[52:55], v[206:209], v[116:119]
	v_mfma_f32_16x16x32_bf16 v[112:115], v[60:63], v[206:209], v[112:115]
	v_mfma_f32_16x16x32_bf16 v[100:103], v[52:55], v[216:219], v[100:103]
	v_mfma_f32_16x16x32_bf16 v[96:99], v[60:63], v[216:219], v[96:99]
	s_setprio 0
	s_barrier
	s_add_i32 s2, s46, s10
	v_lshl_add_u64 v[180:181], s[40:41], 0, v[162:163]
	s_mov_b32 m0, s2
	ds_read_b128 v[176:179], v188 offset:16384
	ds_read_b128 v[190:193], v188 offset:17408
	ds_read_b128 v[194:197], v188 offset:18432
	ds_read_b128 v[198:201], v188 offset:19456
	ds_read_b128 v[202:205], v188 offset:20480
	ds_read_b128 v[206:209], v188 offset:21504
	ds_read_b128 v[212:215], v188 offset:22528
	ds_read_b128 v[216:219], v188 offset:23552
	global_load_lds_dwordx4 v[180:181], off
	s_add_i32 m0, s2, 0x2000
	s_add_u32 s2, s40, 0xb0000
	v_lshl_add_u64 v[228:229], s[40:41], 0, v[166:167]
	s_addc_u32 s3, s41, 0
	s_add_i32 s53, s47, s10
	global_load_lds_dwordx4 v[228:229], off
	s_mov_b32 m0, s53
	v_lshl_add_u64 v[230:231], s[42:43], 0, v[160:161]
	global_load_lds_dwordx4 v162, s[2:3]
	s_add_i32 m0, s53, 0x2000
	v_lshl_add_u64 v[232:233], s[42:43], 0, v[164:165]
	global_load_lds_dwordx4 v166, s[2:3]
	s_mov_b32 m0, s11
	s_nop 0
	global_load_lds_dwordx4 v[230:231], off
	s_mov_b32 m0, s14
	s_nop 0
	global_load_lds_dwordx4 v[232:233], off
	s_waitcnt vmcnt(8)
	s_waitcnt lgkmcnt(0)
	s_barrier
	s_setprio 1
	s_waitcnt lgkmcnt(0)
	v_mfma_f32_16x16x32_bf16 v[92:95], v[32:35], v[176:179], v[92:95]
	v_mfma_f32_16x16x32_bf16 v[88:91], v[40:43], v[176:179], v[88:91]
	v_mfma_f32_16x16x32_bf16 v[76:79], v[32:35], v[194:197], v[76:79]
	v_mfma_f32_16x16x32_bf16 v[72:75], v[40:43], v[194:197], v[72:75]
	v_mfma_f32_16x16x32_bf16 v[28:31], v[32:35], v[202:205], v[28:31]
	v_mfma_f32_16x16x32_bf16 v[24:27], v[40:43], v[202:205], v[24:27]
	v_mfma_f32_16x16x32_bf16 v[12:15], v[32:35], v[212:215], v[12:15]
	v_mfma_f32_16x16x32_bf16 v[8:11], v[40:43], v[212:215], v[8:11]
	v_mfma_f32_16x16x32_bf16 v[92:95], v[36:39], v[190:193], v[92:95]
	v_mfma_f32_16x16x32_bf16 v[88:91], v[44:47], v[190:193], v[88:91]
	v_mfma_f32_16x16x32_bf16 v[76:79], v[36:39], v[198:201], v[76:79]
	v_mfma_f32_16x16x32_bf16 v[72:75], v[44:47], v[198:201], v[72:75]
	v_mfma_f32_16x16x32_bf16 v[28:31], v[36:39], v[206:209], v[28:31]
	v_mfma_f32_16x16x32_bf16 v[24:27], v[44:47], v[206:209], v[24:27]
	v_mfma_f32_16x16x32_bf16 v[12:15], v[36:39], v[216:219], v[12:15]
	v_mfma_f32_16x16x32_bf16 v[8:11], v[44:47], v[216:219], v[8:11]
	s_setprio 0
	s_setprio 1
	v_mfma_f32_16x16x32_bf16 v[20:23], v[48:51], v[202:205], v[20:23]
	v_mfma_f32_16x16x32_bf16 v[16:19], v[56:59], v[202:205], v[16:19]
	v_mfma_f32_16x16x32_bf16 v[4:7], v[48:51], v[212:215], v[4:7]
	v_mfma_f32_16x16x32_bf16 v[0:3], v[56:59], v[212:215], v[0:3]
	v_mfma_f32_16x16x32_bf16 v[32:35], v[48:51], v[176:179], v[84:87]
	v_mfma_f32_16x16x32_bf16 v[36:39], v[56:59], v[176:179], v[80:83]
	v_mfma_f32_16x16x32_bf16 v[40:43], v[48:51], v[194:197], v[68:71]
	v_mfma_f32_16x16x32_bf16 v[44:47], v[56:59], v[194:197], v[64:67]
	v_mfma_f32_16x16x32_bf16 v[20:23], v[52:55], v[206:209], v[20:23]
	v_mfma_f32_16x16x32_bf16 v[16:19], v[60:63], v[206:209], v[16:19]
	v_mfma_f32_16x16x32_bf16 v[4:7], v[52:55], v[216:219], v[4:7]
	v_mfma_f32_16x16x32_bf16 v[0:3], v[60:63], v[216:219], v[0:3]
	v_mfma_f32_16x16x32_bf16 v[32:35], v[52:55], v[190:193], v[32:35]
	v_mfma_f32_16x16x32_bf16 v[36:39], v[60:63], v[190:193], v[36:39]
	v_mfma_f32_16x16x32_bf16 v[40:43], v[52:55], v[198:201], v[40:43]
	v_mfma_f32_16x16x32_bf16 v[44:47], v[60:63], v[198:201], v[44:47]
	s_setprio 0
	s_barrier
	s_add_i32 s53, 0, 0x18000
	s_add_i32 s54, 0, 0x1c000
	v_add_u32_e32 v60, s53, v183
	v_add_u32_e32 v64, s54, v183
	ds_read_b128 v[48:51], v60
	ds_read_b128 v[52:55], v60 offset:1024
	ds_read_b128 v[56:59], v60 offset:2048
	ds_read_b128 v[60:63], v60 offset:3072
	ds_read_b128 v[176:179], v64
	ds_read_b128 v[190:193], v64 offset:1024
	ds_read_b128 v[194:197], v64 offset:2048
	ds_read_b128 v[198:201], v64 offset:3072
	s_add_u32 s2, s42, 0xb0000
	s_addc_u32 s3, s43, 0
	s_mov_b32 m0, s15
	ds_read_b128 v[64:67], v188 offset:32768
	ds_read_b128 v[68:71], v188 offset:33792
	ds_read_b128 v[80:83], v188 offset:34816
	ds_read_b128 v[84:87], v188 offset:35840
	ds_read_b128 v[202:205], v188 offset:36864
	ds_read_b128 v[206:209], v188 offset:37888
	ds_read_b128 v[212:215], v188 offset:38912
	ds_read_b128 v[216:219], v188 offset:39936
	global_load_lds_dwordx4 v160, s[2:3]
	s_mov_b32 m0, s28
	s_nop 0
	global_load_lds_dwordx4 v164, s[2:3]
	s_waitcnt vmcnt(8)
	s_waitcnt lgkmcnt(0)
	s_nop 0
	s_barrier
	s_setprio 1
	s_waitcnt lgkmcnt(0)
	v_mfma_f32_16x16x32_bf16 v[156:159], v[48:51], v[64:67], v[156:159]
	v_mfma_f32_16x16x32_bf16 v[152:155], v[56:59], v[64:67], v[152:155]
	v_mfma_f32_16x16x32_bf16 v[140:143], v[48:51], v[80:83], v[140:143]
	v_mfma_f32_16x16x32_bf16 v[136:139], v[56:59], v[80:83], v[136:139]
	v_mfma_f32_16x16x32_bf16 v[124:127], v[48:51], v[202:205], v[124:127]
	v_mfma_f32_16x16x32_bf16 v[120:123], v[56:59], v[202:205], v[120:123]
	v_mfma_f32_16x16x32_bf16 v[108:111], v[48:51], v[212:215], v[108:111]
	v_mfma_f32_16x16x32_bf16 v[104:107], v[56:59], v[212:215], v[104:107]
	v_mfma_f32_16x16x32_bf16 v[156:159], v[52:55], v[68:71], v[156:159]
	v_mfma_f32_16x16x32_bf16 v[152:155], v[60:63], v[68:71], v[152:155]
	v_mfma_f32_16x16x32_bf16 v[140:143], v[52:55], v[84:87], v[140:143]
	v_mfma_f32_16x16x32_bf16 v[136:139], v[60:63], v[84:87], v[136:139]
	v_mfma_f32_16x16x32_bf16 v[124:127], v[52:55], v[206:209], v[124:127]
	v_mfma_f32_16x16x32_bf16 v[120:123], v[60:63], v[206:209], v[120:123]
	v_mfma_f32_16x16x32_bf16 v[108:111], v[52:55], v[216:219], v[108:111]
	v_mfma_f32_16x16x32_bf16 v[104:107], v[60:63], v[216:219], v[104:107]
	s_setprio 0
	s_setprio 1
	v_mfma_f32_16x16x32_bf16 v[148:151], v[176:179], v[64:67], v[148:151]
	v_mfma_f32_16x16x32_bf16 v[64:67], v[194:197], v[64:67], v[144:147]
	v_mfma_f32_16x16x32_bf16 v[144:147], v[198:201], v[68:71], v[64:67]
	v_mfma_f32_16x16x32_bf16 v[64:67], v[176:179], v[80:83], v[132:135]
	v_mfma_f32_16x16x32_bf16 v[132:135], v[190:193], v[84:87], v[64:67]
	v_mfma_f32_16x16x32_bf16 v[64:67], v[194:197], v[80:83], v[128:131]
	v_mfma_f32_16x16x32_bf16 v[128:131], v[198:201], v[84:87], v[64:67]
	v_mfma_f32_16x16x32_bf16 v[64:67], v[176:179], v[202:205], v[116:119]
	v_mfma_f32_16x16x32_bf16 v[116:119], v[190:193], v[206:209], v[64:67]
	v_mfma_f32_16x16x32_bf16 v[64:67], v[194:197], v[202:205], v[112:115]
	v_mfma_f32_16x16x32_bf16 v[112:115], v[198:201], v[206:209], v[64:67]
	v_mfma_f32_16x16x32_bf16 v[64:67], v[176:179], v[212:215], v[100:103]
	v_mfma_f32_16x16x32_bf16 v[100:103], v[190:193], v[216:219], v[64:67]
	v_mfma_f32_16x16x32_bf16 v[64:67], v[194:197], v[212:215], v[96:99]
	v_mfma_f32_16x16x32_bf16 v[148:151], v[190:193], v[68:71], v[148:151]
	v_mfma_f32_16x16x32_bf16 v[96:99], v[198:201], v[216:219], v[64:67]
	s_setprio 0
	s_barrier
	s_add_i32 s2, s53, s10
	v_lshl_add_u64 v[80:81], v[180:181], 0, s[26:27]
	s_mov_b32 m0, s2
	s_nop 0
	ds_read_b128 v[64:67], v188 offset:49152
	ds_read_b128 v[68:71], v188 offset:50176
	ds_read_b128 v[202:205], v188 offset:51200
	ds_read_b128 v[206:209], v188 offset:52224
	ds_read_b128 v[212:215], v188 offset:53248
	ds_read_b128 v[216:219], v188 offset:54272
	ds_read_b128 v[220:223], v188 offset:55296
	ds_read_b128 v[224:227], v188 offset:56320
	global_load_lds_dwordx4 v[80:81], off
	s_add_i32 m0, s2, 0x2000
	s_add_u32 s2, s40, 0xb0080
	v_lshl_add_u64 v[80:81], v[228:229], 0, s[26:27]
	s_addc_u32 s3, s41, 0
	s_add_i32 s40, s54, s10
	global_load_lds_dwordx4 v[80:81], off
	s_mov_b32 m0, s40
	s_nop 0
	global_load_lds_dwordx4 v162, s[2:3]
	s_add_i32 m0, s40, 0x2000
	s_nop 0
	global_load_lds_dwordx4 v166, s[2:3]
	v_lshl_add_u64 v[80:81], v[230:231], 0, s[26:27]
	s_mov_b32 m0, s33
	s_nop 0
	global_load_lds_dwordx4 v[80:81], off
	v_lshl_add_u64 v[80:81], v[232:233], 0, s[26:27]
	s_mov_b32 m0, s44
	s_nop 0
	global_load_lds_dwordx4 v[80:81], off
	s_waitcnt vmcnt(8)
	s_waitcnt lgkmcnt(0)
	s_nop 0
	s_barrier
	s_setprio 1
	s_waitcnt lgkmcnt(0)
	v_mfma_f32_16x16x32_bf16 v[80:83], v[48:51], v[64:67], v[92:95]
	v_mfma_f32_16x16x32_bf16 v[92:95], v[52:55], v[68:71], v[80:83]
	v_mfma_f32_16x16x32_bf16 v[80:83], v[56:59], v[64:67], v[88:91]
	v_mfma_f32_16x16x32_bf16 v[76:79], v[48:51], v[202:205], v[76:79]
	v_mfma_f32_16x16x32_bf16 v[72:75], v[56:59], v[202:205], v[72:75]
	v_mfma_f32_16x16x32_bf16 v[28:31], v[48:51], v[212:215], v[28:31]
	v_mfma_f32_16x16x32_bf16 v[24:27], v[56:59], v[212:215], v[24:27]
	v_mfma_f32_16x16x32_bf16 v[12:15], v[48:51], v[220:223], v[12:15]
	v_mfma_f32_16x16x32_bf16 v[8:11], v[56:59], v[220:223], v[8:11]
	v_mfma_f32_16x16x32_bf16 v[88:91], v[60:63], v[68:71], v[80:83]
	v_mfma_f32_16x16x32_bf16 v[76:79], v[52:55], v[206:209], v[76:79]
	v_mfma_f32_16x16x32_bf16 v[72:75], v[60:63], v[206:209], v[72:75]
	v_mfma_f32_16x16x32_bf16 v[28:31], v[52:55], v[216:219], v[28:31]
	v_mfma_f32_16x16x32_bf16 v[24:27], v[60:63], v[216:219], v[24:27]
	v_mfma_f32_16x16x32_bf16 v[12:15], v[52:55], v[224:227], v[12:15]
	v_mfma_f32_16x16x32_bf16 v[8:11], v[60:63], v[224:227], v[8:11]
	s_setprio 0
	s_setprio 1
	v_mfma_f32_16x16x32_bf16 v[32:35], v[176:179], v[64:67], v[32:35]
	v_mfma_f32_16x16x32_bf16 v[84:87], v[190:193], v[68:71], v[32:35]
	v_mfma_f32_16x16x32_bf16 v[32:35], v[194:197], v[64:67], v[36:39]
	v_mfma_f32_16x16x32_bf16 v[80:83], v[198:201], v[68:71], v[32:35]
	v_mfma_f32_16x16x32_bf16 v[32:35], v[176:179], v[202:205], v[40:43]
	v_mfma_f32_16x16x32_bf16 v[68:71], v[190:193], v[206:209], v[32:35]
	v_mfma_f32_16x16x32_bf16 v[32:35], v[194:197], v[202:205], v[44:47]
	v_mfma_f32_16x16x32_bf16 v[20:23], v[176:179], v[212:215], v[20:23]
	v_mfma_f32_16x16x32_bf16 v[16:19], v[194:197], v[212:215], v[16:19]
	v_mfma_f32_16x16x32_bf16 v[4:7], v[176:179], v[220:223], v[4:7]
	v_mfma_f32_16x16x32_bf16 v[0:3], v[194:197], v[220:223], v[0:3]
	v_mfma_f32_16x16x32_bf16 v[64:67], v[198:201], v[206:209], v[32:35]
	v_mfma_f32_16x16x32_bf16 v[20:23], v[190:193], v[216:219], v[20:23]
	v_mfma_f32_16x16x32_bf16 v[16:19], v[198:201], v[216:219], v[16:19]
	v_mfma_f32_16x16x32_bf16 v[4:7], v[190:193], v[224:227], v[4:7]
	v_mfma_f32_16x16x32_bf16 v[0:3], v[198:201], v[224:227], v[0:3]
	s_setprio 0
	s_barrier
	s_add_i32 s52, s52, 2
	s_add_u32 s1, s1, 0x100
	s_addc_u32 s51, s51, 0
	s_cmp_gt_u32 s52, 41
	s_mov_b64 s[2:3], s[38:39]
	s_cbranch_scc0 .LBB0_617
	s_and_b64 vcc, exec, s[34:35]
	s_cbranch_vccz .LBB0_620
	s_barrier

.LBB0_704:
	ds_read_b128 v[128:131], v214
	ds_read_b128 v[132:135], v214 offset:1024
	ds_read_b128 v[136:139], v214 offset:2048
	ds_read_b128 v[140:143], v214 offset:3072
	ds_read_b128 v[144:147], v215
	ds_read_b128 v[148:151], v215 offset:1024
	ds_read_b128 v[168:171], v215 offset:2048
	ds_read_b128 v[172:175], v215 offset:3072
	s_add_u32 s6, s4, 0xfffc0080
	s_addc_u32 s7, s5, -1
	s_cmp_eq_u32 s57, 12
	s_cselect_b32 s63, s3, s7
	s_cselect_b32 s62, s11, s6
	s_cselect_b32 s7, s14, s55
	s_cselect_b32 s6, s15, s28
	s_add_i32 m0, s64, 0xc000
	ds_read_b128 v[176:179], v216
	ds_read_b128 v[180:183], v216 offset:1024
	ds_read_b128 v[184:187], v216 offset:2048
	ds_read_b128 v[188:191], v216 offset:3072
	ds_read_b128 v[192:195], v216 offset:4096
	ds_read_b128 v[196:199], v216 offset:5120
	ds_read_b128 v[200:203], v216 offset:6144
	ds_read_b128 v[204:207], v216 offset:7168
	global_load_lds_dwordx4 v160, s[4:5]
	s_add_i32 m0, s64, 0xe000
	s_nop 0
	global_load_lds_dwordx4 v162, s[4:5]
	s_waitcnt vmcnt(8)
	s_waitcnt lgkmcnt(0)
	s_nop 0
	s_barrier
	s_setprio 1
	s_waitcnt lgkmcnt(0)
	v_mfma_f32_16x16x32_bf16 v[124:127], v[128:131], v[176:179], v[124:127]
	v_mfma_f32_16x16x32_bf16 v[120:123], v[136:139], v[176:179], v[120:123]
	v_mfma_f32_16x16x32_bf16 v[116:119], v[128:131], v[184:187], v[116:119]
	v_mfma_f32_16x16x32_bf16 v[112:115], v[136:139], v[184:187], v[112:115]
	v_mfma_f32_16x16x32_bf16 v[108:111], v[128:131], v[192:195], v[108:111]
	v_mfma_f32_16x16x32_bf16 v[100:103], v[136:139], v[192:195], v[100:103]
	v_mfma_f32_16x16x32_bf16 v[88:91], v[128:131], v[200:203], v[88:91]
	v_mfma_f32_16x16x32_bf16 v[80:83], v[136:139], v[200:203], v[80:83]
	v_mfma_f32_16x16x32_bf16 v[124:127], v[132:135], v[180:183], v[124:127]
	v_mfma_f32_16x16x32_bf16 v[120:123], v[140:143], v[180:183], v[120:123]
	v_mfma_f32_16x16x32_bf16 v[116:119], v[132:135], v[188:191], v[116:119]
	v_mfma_f32_16x16x32_bf16 v[112:115], v[140:143], v[188:191], v[112:115]
	v_mfma_f32_16x16x32_bf16 v[108:111], v[132:135], v[196:199], v[108:111]
	v_mfma_f32_16x16x32_bf16 v[100:103], v[140:143], v[196:199], v[100:103]
	v_mfma_f32_16x16x32_bf16 v[88:91], v[132:135], v[204:207], v[88:91]
	v_mfma_f32_16x16x32_bf16 v[80:83], v[140:143], v[204:207], v[80:83]
	s_setprio 0
	s_setprio 1
	v_mfma_f32_16x16x32_bf16 v[104:107], v[144:147], v[176:179], v[104:107]
	v_mfma_f32_16x16x32_bf16 v[96:99], v[168:171], v[176:179], v[96:99]
	v_mfma_f32_16x16x32_bf16 v[92:95], v[144:147], v[184:187], v[92:95]
	v_mfma_f32_16x16x32_bf16 v[84:87], v[168:171], v[184:187], v[84:87]
	v_mfma_f32_16x16x32_bf16 v[76:79], v[144:147], v[192:195], v[76:79]
	v_mfma_f32_16x16x32_bf16 v[72:75], v[168:171], v[192:195], v[72:75]
	v_mfma_f32_16x16x32_bf16 v[68:71], v[144:147], v[200:203], v[68:71]
	v_mfma_f32_16x16x32_bf16 v[64:67], v[168:171], v[200:203], v[64:67]
	v_mfma_f32_16x16x32_bf16 v[104:107], v[148:151], v[180:183], v[104:107]
	v_mfma_f32_16x16x32_bf16 v[96:99], v[172:175], v[180:183], v[96:99]
	v_mfma_f32_16x16x32_bf16 v[92:95], v[148:151], v[188:191], v[92:95]
	v_mfma_f32_16x16x32_bf16 v[84:87], v[172:175], v[188:191], v[84:87]
	v_mfma_f32_16x16x32_bf16 v[76:79], v[148:151], v[196:199], v[76:79]
	v_mfma_f32_16x16x32_bf16 v[72:75], v[172:175], v[196:199], v[72:75]
	v_mfma_f32_16x16x32_bf16 v[68:71], v[148:151], v[204:207], v[68:71]
	v_mfma_f32_16x16x32_bf16 v[64:67], v[172:175], v[204:207], v[64:67]
	s_setprio 0
	s_barrier
	s_add_i32 s68, s79, s33
	v_lshl_add_u64 v[208:209], s[6:7], 0, v[156:157]
	s_mov_b32 m0, s68
	ds_read_b128 v[176:179], v216 offset:16384
	ds_read_b128 v[180:183], v216 offset:17408
	ds_read_b128 v[184:187], v216 offset:18432
	ds_read_b128 v[188:191], v216 offset:19456
	ds_read_b128 v[192:195], v216 offset:20480
	ds_read_b128 v[196:199], v216 offset:21504
	ds_read_b128 v[200:203], v216 offset:22528
	ds_read_b128 v[204:207], v216 offset:23552
	global_load_lds_dwordx4 v[208:209], off
	s_add_i32 m0, s68, 0x2000
	s_add_u32 s84, s6, 0x40000
	v_lshl_add_u64 v[220:221], s[6:7], 0, v[152:153]
	s_addc_u32 s85, s7, 0
	s_add_i32 s68, s80, s33
	global_load_lds_dwordx4 v[220:221], off
	s_mov_b32 m0, s68
	v_lshl_add_u64 v[224:225], s[62:63], 0, v[154:155]
	global_load_lds_dwordx4 v156, s[84:85]
	s_add_i32 m0, s68, 0x2000
	s_nop 0
	global_load_lds_dwordx4 v152, s[84:85]
	v_lshl_add_u64 v[222:223], s[62:63], 0, v[158:159]
	s_mov_b32 m0, s64
	s_nop 0
	global_load_lds_dwordx4 v[222:223], off
	s_mov_b32 m0, s65
	s_nop 0
	global_load_lds_dwordx4 v[224:225], off
	s_waitcnt vmcnt(8)
	s_waitcnt lgkmcnt(0)
	s_nop 0
	s_barrier
	s_setprio 1
	s_waitcnt lgkmcnt(0)
	v_mfma_f32_16x16x32_bf16 v[60:63], v[128:131], v[176:179], v[60:63]
	v_mfma_f32_16x16x32_bf16 v[56:59], v[136:139], v[176:179], v[56:59]
	v_mfma_f32_16x16x32_bf16 v[52:55], v[128:131], v[184:187], v[52:55]
	v_mfma_f32_16x16x32_bf16 v[48:51], v[136:139], v[184:187], v[48:51]
	v_mfma_f32_16x16x32_bf16 v[40:43], v[128:131], v[192:195], v[40:43]
	v_mfma_f32_16x16x32_bf16 v[32:35], v[136:139], v[192:195], v[32:35]
	v_mfma_f32_16x16x32_bf16 v[20:23], v[128:131], v[200:203], v[20:23]
	v_mfma_f32_16x16x32_bf16 v[16:19], v[136:139], v[200:203], v[16:19]
	v_mfma_f32_16x16x32_bf16 v[60:63], v[132:135], v[180:183], v[60:63]
	v_mfma_f32_16x16x32_bf16 v[56:59], v[140:143], v[180:183], v[56:59]
	v_mfma_f32_16x16x32_bf16 v[52:55], v[132:135], v[188:191], v[52:55]
	v_mfma_f32_16x16x32_bf16 v[48:51], v[140:143], v[188:191], v[48:51]
	v_mfma_f32_16x16x32_bf16 v[40:43], v[132:135], v[196:199], v[40:43]
	v_mfma_f32_16x16x32_bf16 v[32:35], v[140:143], v[196:199], v[32:35]
	v_mfma_f32_16x16x32_bf16 v[20:23], v[132:135], v[204:207], v[20:23]
	v_mfma_f32_16x16x32_bf16 v[16:19], v[140:143], v[204:207], v[16:19]
	s_setprio 0
	s_setprio 1
	v_mfma_f32_16x16x32_bf16 v[44:47], v[144:147], v[176:179], v[44:47]
	v_mfma_f32_16x16x32_bf16 v[36:39], v[168:171], v[176:179], v[36:39]
	v_mfma_f32_16x16x32_bf16 v[28:31], v[144:147], v[184:187], v[28:31]
	v_mfma_f32_16x16x32_bf16 v[24:27], v[168:171], v[184:187], v[24:27]
	v_mfma_f32_16x16x32_bf16 v[12:15], v[144:147], v[192:195], v[12:15]
	v_mfma_f32_16x16x32_bf16 v[8:11], v[168:171], v[192:195], v[8:11]
	v_mfma_f32_16x16x32_bf16 v[4:7], v[144:147], v[200:203], v[4:7]
	v_mfma_f32_16x16x32_bf16 v[0:3], v[168:171], v[200:203], v[0:3]
	v_mfma_f32_16x16x32_bf16 v[44:47], v[148:151], v[180:183], v[44:47]
	v_mfma_f32_16x16x32_bf16 v[36:39], v[172:175], v[180:183], v[36:39]
	v_mfma_f32_16x16x32_bf16 v[28:31], v[148:151], v[188:191], v[28:31]
	v_mfma_f32_16x16x32_bf16 v[24:27], v[172:175], v[188:191], v[24:27]
	v_mfma_f32_16x16x32_bf16 v[12:15], v[148:151], v[196:199], v[12:15]
	v_mfma_f32_16x16x32_bf16 v[8:11], v[172:175], v[196:199], v[8:11]
	v_mfma_f32_16x16x32_bf16 v[4:7], v[148:151], v[204:207], v[4:7]
	v_mfma_f32_16x16x32_bf16 v[0:3], v[172:175], v[204:207], v[0:3]
	s_setprio 0
	s_barrier
	s_add_i32 s68, 0, 0x18000
	s_add_i32 s83, 0, 0x1c000
	v_add_u32_e32 v140, s68, v213
	v_add_u32_e32 v172, s83, v213
	ds_read_b128 v[128:131], v140
	ds_read_b128 v[132:135], v140 offset:1024
	ds_read_b128 v[136:139], v140 offset:2048
	ds_read_b128 v[140:143], v140 offset:3072
	ds_read_b128 v[144:147], v172
	ds_read_b128 v[148:151], v172 offset:1024
	ds_read_b128 v[168:171], v172 offset:2048
	ds_read_b128 v[172:175], v172 offset:3072
	s_add_u32 s62, s62, 0x40000
	s_addc_u32 s63, s63, 0
	s_mov_b32 m0, s66
	ds_read_b128 v[176:179], v216 offset:32768
	ds_read_b128 v[180:183], v216 offset:33792
	ds_read_b128 v[184:187], v216 offset:34816
	ds_read_b128 v[188:191], v216 offset:35840
	ds_read_b128 v[192:195], v216 offset:36864
	ds_read_b128 v[196:199], v216 offset:37888
	ds_read_b128 v[200:203], v216 offset:38912
	ds_read_b128 v[204:207], v216 offset:39936
	global_load_lds_dwordx4 v158, s[62:63]
	s_mov_b32 m0, s67
	s_nop 0
	global_load_lds_dwordx4 v154, s[62:63]
	s_waitcnt vmcnt(8)
	s_waitcnt lgkmcnt(0)
	s_nop 0
	s_barrier
	s_setprio 1
	s_waitcnt lgkmcnt(0)
	v_mfma_f32_16x16x32_bf16 v[124:127], v[128:131], v[176:179], v[124:127]
	v_mfma_f32_16x16x32_bf16 v[120:123], v[136:139], v[176:179], v[120:123]
	v_mfma_f32_16x16x32_bf16 v[116:119], v[128:131], v[184:187], v[116:119]
	v_mfma_f32_16x16x32_bf16 v[112:115], v[136:139], v[184:187], v[112:115]
	v_mfma_f32_16x16x32_bf16 v[108:111], v[128:131], v[192:195], v[108:111]
	v_mfma_f32_16x16x32_bf16 v[100:103], v[136:139], v[192:195], v[100:103]
	v_mfma_f32_16x16x32_bf16 v[88:91], v[128:131], v[200:203], v[88:91]
	v_mfma_f32_16x16x32_bf16 v[80:83], v[136:139], v[200:203], v[80:83]
	v_mfma_f32_16x16x32_bf16 v[124:127], v[132:135], v[180:183], v[124:127]
	v_mfma_f32_16x16x32_bf16 v[120:123], v[140:143], v[180:183], v[120:123]
	v_mfma_f32_16x16x32_bf16 v[116:119], v[132:135], v[188:191], v[116:119]
	v_mfma_f32_16x16x32_bf16 v[112:115], v[140:143], v[188:191], v[112:115]
	v_mfma_f32_16x16x32_bf16 v[108:111], v[132:135], v[196:199], v[108:111]
	v_mfma_f32_16x16x32_bf16 v[100:103], v[140:143], v[196:199], v[100:103]
	v_mfma_f32_16x16x32_bf16 v[88:91], v[132:135], v[204:207], v[88:91]
	v_mfma_f32_16x16x32_bf16 v[80:83], v[140:143], v[204:207], v[80:83]
	s_setprio 0
	s_setprio 1
	v_mfma_f32_16x16x32_bf16 v[104:107], v[144:147], v[176:179], v[104:107]
	v_mfma_f32_16x16x32_bf16 v[96:99], v[168:171], v[176:179], v[96:99]
	v_mfma_f32_16x16x32_bf16 v[92:95], v[144:147], v[184:187], v[92:95]
	v_mfma_f32_16x16x32_bf16 v[84:87], v[168:171], v[184:187], v[84:87]
	v_mfma_f32_16x16x32_bf16 v[76:79], v[144:147], v[192:195], v[76:79]
	v_mfma_f32_16x16x32_bf16 v[72:75], v[168:171], v[192:195], v[72:75]
	v_mfma_f32_16x16x32_bf16 v[68:71], v[144:147], v[200:203], v[68:71]
	v_mfma_f32_16x16x32_bf16 v[64:67], v[168:171], v[200:203], v[64:67]
	v_mfma_f32_16x16x32_bf16 v[104:107], v[148:151], v[180:183], v[104:107]
	v_mfma_f32_16x16x32_bf16 v[96:99], v[172:175], v[180:183], v[96:99]
	v_mfma_f32_16x16x32_bf16 v[92:95], v[148:151], v[188:191], v[92:95]
	v_mfma_f32_16x16x32_bf16 v[84:87], v[172:175], v[188:191], v[84:87]
	v_mfma_f32_16x16x32_bf16 v[76:79], v[148:151], v[196:199], v[76:79]
	v_mfma_f32_16x16x32_bf16 v[72:75], v[172:175], v[196:199], v[72:75]
	v_mfma_f32_16x16x32_bf16 v[68:71], v[148:151], v[204:207], v[68:71]
	v_mfma_f32_16x16x32_bf16 v[64:67], v[172:175], v[204:207], v[64:67]
	s_setprio 0
	s_barrier
	s_add_i32 s62, s68, s33
	v_lshl_add_u64 v[208:209], v[208:209], 0, s[42:43]
	s_mov_b32 m0, s62
	ds_read_b128 v[176:179], v216 offset:49152
	ds_read_b128 v[180:183], v216 offset:50176
	ds_read_b128 v[184:187], v216 offset:51200
	ds_read_b128 v[188:191], v216 offset:52224
	ds_read_b128 v[192:195], v216 offset:53248
	ds_read_b128 v[196:199], v216 offset:54272
	ds_read_b128 v[200:203], v216 offset:55296
	ds_read_b128 v[204:207], v216 offset:56320
	global_load_lds_dwordx4 v[208:209], off
	s_add_i32 m0, s62, 0x2000
	s_add_u32 s6, s6, 0x40080
	v_lshl_add_u64 v[208:209], v[220:221], 0, s[42:43]
	s_addc_u32 s7, s7, 0
	s_add_i32 s62, s83, s33
	global_load_lds_dwordx4 v[208:209], off
	s_mov_b32 m0, s62
	s_nop 0
	global_load_lds_dwordx4 v156, s[6:7]
	s_add_i32 m0, s62, 0x2000
	s_nop 0
	global_load_lds_dwordx4 v152, s[6:7]
	v_lshl_add_u64 v[208:209], v[222:223], 0, s[42:43]
	s_mov_b32 m0, s75
	s_nop 0
	global_load_lds_dwordx4 v[208:209], off
	v_lshl_add_u64 v[208:209], v[224:225], 0, s[42:43]
	s_mov_b32 m0, s76
	s_nop 0
	global_load_lds_dwordx4 v[208:209], off
	s_waitcnt vmcnt(8)
	s_waitcnt lgkmcnt(0)
	s_barrier
	s_setprio 1
	s_waitcnt lgkmcnt(0)
	v_mfma_f32_16x16x32_bf16 v[60:63], v[128:131], v[176:179], v[60:63]
	v_mfma_f32_16x16x32_bf16 v[56:59], v[136:139], v[176:179], v[56:59]
	v_mfma_f32_16x16x32_bf16 v[52:55], v[128:131], v[184:187], v[52:55]
	v_mfma_f32_16x16x32_bf16 v[48:51], v[136:139], v[184:187], v[48:51]
	v_mfma_f32_16x16x32_bf16 v[40:43], v[128:131], v[192:195], v[40:43]
	v_mfma_f32_16x16x32_bf16 v[32:35], v[136:139], v[192:195], v[32:35]
	v_mfma_f32_16x16x32_bf16 v[20:23], v[128:131], v[200:203], v[20:23]
	v_mfma_f32_16x16x32_bf16 v[16:19], v[136:139], v[200:203], v[16:19]
	v_mfma_f32_16x16x32_bf16 v[60:63], v[132:135], v[180:183], v[60:63]
	v_mfma_f32_16x16x32_bf16 v[56:59], v[140:143], v[180:183], v[56:59]
	v_mfma_f32_16x16x32_bf16 v[52:55], v[132:135], v[188:191], v[52:55]
	v_mfma_f32_16x16x32_bf16 v[48:51], v[140:143], v[188:191], v[48:51]
	v_mfma_f32_16x16x32_bf16 v[40:43], v[132:135], v[196:199], v[40:43]
	v_mfma_f32_16x16x32_bf16 v[32:35], v[140:143], v[196:199], v[32:35]
	v_mfma_f32_16x16x32_bf16 v[20:23], v[132:135], v[204:207], v[20:23]
	v_mfma_f32_16x16x32_bf16 v[16:19], v[140:143], v[204:207], v[16:19]
	s_setprio 0
	s_setprio 1
	v_mfma_f32_16x16x32_bf16 v[44:47], v[144:147], v[176:179], v[44:47]
	v_mfma_f32_16x16x32_bf16 v[36:39], v[168:171], v[176:179], v[36:39]
	v_mfma_f32_16x16x32_bf16 v[28:31], v[144:147], v[184:187], v[28:31]
	v_mfma_f32_16x16x32_bf16 v[24:27], v[168:171], v[184:187], v[24:27]
	v_mfma_f32_16x16x32_bf16 v[12:15], v[144:147], v[192:195], v[12:15]
	v_mfma_f32_16x16x32_bf16 v[8:11], v[168:171], v[192:195], v[8:11]
	v_mfma_f32_16x16x32_bf16 v[4:7], v[144:147], v[200:203], v[4:7]
	v_mfma_f32_16x16x32_bf16 v[0:3], v[168:171], v[200:203], v[0:3]
	v_mfma_f32_16x16x32_bf16 v[44:47], v[148:151], v[180:183], v[44:47]
	v_mfma_f32_16x16x32_bf16 v[36:39], v[172:175], v[180:183], v[36:39]
	v_mfma_f32_16x16x32_bf16 v[28:31], v[148:151], v[188:191], v[28:31]
	v_mfma_f32_16x16x32_bf16 v[24:27], v[172:175], v[188:191], v[24:27]
	v_mfma_f32_16x16x32_bf16 v[12:15], v[148:151], v[196:199], v[12:15]
	v_mfma_f32_16x16x32_bf16 v[8:11], v[172:175], v[196:199], v[8:11]
	v_mfma_f32_16x16x32_bf16 v[4:7], v[148:151], v[204:207], v[4:7]
	v_mfma_f32_16x16x32_bf16 v[0:3], v[172:175], v[204:207], v[0:3]
	s_setprio 0
	s_barrier
	s_add_i32 s57, s57, 2
	s_add_u32 s4, s4, 0x100
	s_addc_u32 s5, s5, 0
	s_add_u32 s28, s28, 0x100
	s_addc_u32 s55, s55, 0
	s_cmp_gt_u32 s57, 13
	s_cbranch_scc0 .LBB0_704
	s_and_b64 vcc, exec, s[44:45]
	s_cbranch_vccz .LBB0_707
	s_barrier

.LBB0_862:
	ds_read_b128 v[152:155], v159
	ds_read_b128 v[164:167], v159 offset:1024
	ds_read_b128 v[168:171], v159 offset:2048
	ds_read_b128 v[172:175], v159 offset:3072
	ds_read_b128 v[176:179], v160
	ds_read_b128 v[180:183], v160 offset:1024
	ds_read_b128 v[184:187], v160 offset:2048
	ds_read_b128 v[188:191], v160 offset:3072
	s_add_u32 s4, s40, 0x100
	s_addc_u32 s5, s41, 0
	s_cmp_eq_u32 s58, 2
	s_cselect_b32 s45, s35, s5
	s_cselect_b32 s44, s34, s4
	s_cselect_b32 s43, s37, s57
	s_cselect_b32 s42, s36, s56
	s_add_i32 m0, s11, 0xc000
	ds_read_b128 v[192:195], v161
	ds_read_b128 v[196:199], v161 offset:1024
	ds_read_b128 v[200:203], v161 offset:2048
	ds_read_b128 v[204:207], v161 offset:3072
	ds_read_b128 v[212:215], v161 offset:4096
	ds_read_b128 v[216:219], v161 offset:5120
	ds_read_b128 v[220:223], v161 offset:6144
	ds_read_b128 v[224:227], v161 offset:7168
	global_load_lds_dwordx4 v144, s[40:41]
	s_add_i32 m0, s11, 0xe000
	s_nop 0
	global_load_lds_dwordx4 v146, s[40:41]
	s_waitcnt vmcnt(8)
	s_waitcnt lgkmcnt(0)
	s_nop 0
	s_barrier
	s_setprio 1
	s_waitcnt lgkmcnt(0)
	v_mfma_f32_16x16x32_bf16 v[124:127], v[152:155], v[192:195], v[124:127]
	v_mfma_f32_16x16x32_bf16 v[120:123], v[168:171], v[192:195], v[120:123]
	v_mfma_f32_16x16x32_bf16 v[108:111], v[152:155], v[200:203], v[108:111]
	v_mfma_f32_16x16x32_bf16 v[104:107], v[168:171], v[200:203], v[104:107]
	v_mfma_f32_16x16x32_bf16 v[92:95], v[152:155], v[212:215], v[92:95]
	v_mfma_f32_16x16x32_bf16 v[88:91], v[168:171], v[212:215], v[88:91]
	v_mfma_f32_16x16x32_bf16 v[76:79], v[152:155], v[220:223], v[76:79]
	v_mfma_f32_16x16x32_bf16 v[72:75], v[168:171], v[220:223], v[72:75]
	v_mfma_f32_16x16x32_bf16 v[124:127], v[164:167], v[196:199], v[124:127]
	v_mfma_f32_16x16x32_bf16 v[120:123], v[172:175], v[196:199], v[120:123]
	v_mfma_f32_16x16x32_bf16 v[108:111], v[164:167], v[204:207], v[108:111]
	v_mfma_f32_16x16x32_bf16 v[104:107], v[172:175], v[204:207], v[104:107]
	v_mfma_f32_16x16x32_bf16 v[92:95], v[164:167], v[216:219], v[92:95]
	v_mfma_f32_16x16x32_bf16 v[88:91], v[172:175], v[216:219], v[88:91]
	v_mfma_f32_16x16x32_bf16 v[76:79], v[164:167], v[224:227], v[76:79]
	v_mfma_f32_16x16x32_bf16 v[72:75], v[172:175], v[224:227], v[72:75]
	s_setprio 0
	s_setprio 1
	v_mfma_f32_16x16x32_bf16 v[116:119], v[176:179], v[192:195], v[116:119]
	v_mfma_f32_16x16x32_bf16 v[112:115], v[184:187], v[192:195], v[112:115]
	v_mfma_f32_16x16x32_bf16 v[100:103], v[176:179], v[200:203], v[100:103]
	v_mfma_f32_16x16x32_bf16 v[96:99], v[184:187], v[200:203], v[96:99]
	v_mfma_f32_16x16x32_bf16 v[84:87], v[176:179], v[212:215], v[84:87]
	v_mfma_f32_16x16x32_bf16 v[80:83], v[184:187], v[212:215], v[80:83]
	v_mfma_f32_16x16x32_bf16 v[68:71], v[176:179], v[220:223], v[68:71]
	v_mfma_f32_16x16x32_bf16 v[64:67], v[184:187], v[220:223], v[64:67]
	v_mfma_f32_16x16x32_bf16 v[116:119], v[180:183], v[196:199], v[116:119]
	v_mfma_f32_16x16x32_bf16 v[112:115], v[188:191], v[196:199], v[112:115]
	v_mfma_f32_16x16x32_bf16 v[100:103], v[180:183], v[204:207], v[100:103]
	v_mfma_f32_16x16x32_bf16 v[96:99], v[188:191], v[204:207], v[96:99]
	v_mfma_f32_16x16x32_bf16 v[84:87], v[180:183], v[216:219], v[84:87]
	v_mfma_f32_16x16x32_bf16 v[80:83], v[188:191], v[216:219], v[80:83]
	v_mfma_f32_16x16x32_bf16 v[68:71], v[180:183], v[224:227], v[68:71]
	v_mfma_f32_16x16x32_bf16 v[64:67], v[188:191], v[224:227], v[64:67]
	s_setprio 0
	s_barrier
	s_add_i32 s40, s48, s10
	v_lshl_add_u64 v[156:157], s[42:43], 0, v[130:131]
	s_mov_b32 m0, s40
	ds_read_b128 v[192:195], v161 offset:16384
	ds_read_b128 v[196:199], v161 offset:17408
	ds_read_b128 v[200:203], v161 offset:18432
	ds_read_b128 v[204:207], v161 offset:19456
	ds_read_b128 v[212:215], v161 offset:20480
	ds_read_b128 v[216:219], v161 offset:21504
	ds_read_b128 v[220:223], v161 offset:22528
	ds_read_b128 v[224:227], v161 offset:23552
	global_load_lds_dwordx4 v[156:157], off
	s_add_i32 m0, s40, 0x2000
	s_add_u32 s40, s42, 0x18000
	v_lshl_add_u64 v[208:209], s[42:43], 0, v[134:135]
	s_addc_u32 s41, s43, 0
	s_add_i32 s59, s49, s10
	global_load_lds_dwordx4 v[208:209], off
	s_mov_b32 m0, s59
	v_lshl_add_u64 v[230:231], s[44:45], 0, v[132:133]
	global_load_lds_dwordx4 v130, s[40:41]
	s_add_i32 m0, s59, 0x2000
	s_nop 0
	global_load_lds_dwordx4 v134, s[40:41]
	v_lshl_add_u64 v[228:229], s[44:45], 0, v[128:129]
	s_mov_b32 m0, s11
	s_nop 0
	global_load_lds_dwordx4 v[228:229], off
	s_mov_b32 m0, s14
	s_nop 0
	global_load_lds_dwordx4 v[230:231], off
	s_waitcnt vmcnt(8)
	s_waitcnt lgkmcnt(0)
	s_nop 0
	s_barrier
	s_setprio 1
	s_waitcnt lgkmcnt(0)
	v_mfma_f32_16x16x32_bf16 v[60:63], v[152:155], v[192:195], v[60:63]
	v_mfma_f32_16x16x32_bf16 v[56:59], v[168:171], v[192:195], v[56:59]
	v_mfma_f32_16x16x32_bf16 v[44:47], v[152:155], v[200:203], v[44:47]
	v_mfma_f32_16x16x32_bf16 v[40:43], v[168:171], v[200:203], v[40:43]
	v_mfma_f32_16x16x32_bf16 v[28:31], v[152:155], v[212:215], v[28:31]
	v_mfma_f32_16x16x32_bf16 v[24:27], v[168:171], v[212:215], v[24:27]
	v_mfma_f32_16x16x32_bf16 v[12:15], v[152:155], v[220:223], v[12:15]
	v_mfma_f32_16x16x32_bf16 v[8:11], v[168:171], v[220:223], v[8:11]
	v_mfma_f32_16x16x32_bf16 v[60:63], v[164:167], v[196:199], v[60:63]
	v_mfma_f32_16x16x32_bf16 v[56:59], v[172:175], v[196:199], v[56:59]
	v_mfma_f32_16x16x32_bf16 v[44:47], v[164:167], v[204:207], v[44:47]
	v_mfma_f32_16x16x32_bf16 v[40:43], v[172:175], v[204:207], v[40:43]
	v_mfma_f32_16x16x32_bf16 v[28:31], v[164:167], v[216:219], v[28:31]
	v_mfma_f32_16x16x32_bf16 v[24:27], v[172:175], v[216:219], v[24:27]
	v_mfma_f32_16x16x32_bf16 v[12:15], v[164:167], v[224:227], v[12:15]
	v_mfma_f32_16x16x32_bf16 v[8:11], v[172:175], v[224:227], v[8:11]
	s_setprio 0
	s_setprio 1
	v_mfma_f32_16x16x32_bf16 v[52:55], v[176:179], v[192:195], v[52:55]
	v_mfma_f32_16x16x32_bf16 v[48:51], v[184:187], v[192:195], v[48:51]
	v_mfma_f32_16x16x32_bf16 v[36:39], v[176:179], v[200:203], v[36:39]
	v_mfma_f32_16x16x32_bf16 v[32:35], v[184:187], v[200:203], v[32:35]
	v_mfma_f32_16x16x32_bf16 v[20:23], v[176:179], v[212:215], v[20:23]
	v_mfma_f32_16x16x32_bf16 v[16:19], v[184:187], v[212:215], v[16:19]
	v_mfma_f32_16x16x32_bf16 v[4:7], v[176:179], v[220:223], v[4:7]
	v_mfma_f32_16x16x32_bf16 v[0:3], v[184:187], v[220:223], v[0:3]
	v_mfma_f32_16x16x32_bf16 v[52:55], v[180:183], v[196:199], v[52:55]
	v_mfma_f32_16x16x32_bf16 v[48:51], v[188:191], v[196:199], v[48:51]
	v_mfma_f32_16x16x32_bf16 v[36:39], v[180:183], v[204:207], v[36:39]
	v_mfma_f32_16x16x32_bf16 v[32:35], v[188:191], v[204:207], v[32:35]
	v_mfma_f32_16x16x32_bf16 v[20:23], v[180:183], v[216:219], v[20:23]
	v_mfma_f32_16x16x32_bf16 v[16:19], v[188:191], v[216:219], v[16:19]
	v_mfma_f32_16x16x32_bf16 v[4:7], v[180:183], v[224:227], v[4:7]
	v_mfma_f32_16x16x32_bf16 v[0:3], v[188:191], v[224:227], v[0:3]
	s_setprio 0
	s_barrier
	s_add_i32 s59, 0, 0x18000
	v_add_u32_e32 v163, s59, v158
	s_add_i32 s60, 0, 0x1c000
	ds_read_b128 v[152:155], v163
	ds_read_b128 v[164:167], v163 offset:1024
	ds_read_b128 v[168:171], v163 offset:2048
	ds_read_b128 v[172:175], v163 offset:3072
	v_add_u32_e32 v163, s60, v158
	ds_read_b128 v[176:179], v163
	ds_read_b128 v[180:183], v163 offset:1024
	ds_read_b128 v[184:187], v163 offset:2048
	ds_read_b128 v[188:191], v163 offset:3072
	s_add_u32 s40, s44, 0x18000
	s_addc_u32 s41, s45, 0
	s_mov_b32 m0, s15
	ds_read_b128 v[192:195], v161 offset:32768
	ds_read_b128 v[196:199], v161 offset:33792
	ds_read_b128 v[200:203], v161 offset:34816
	ds_read_b128 v[204:207], v161 offset:35840
	ds_read_b128 v[212:215], v161 offset:36864
	ds_read_b128 v[216:219], v161 offset:37888
	ds_read_b128 v[220:223], v161 offset:38912
	ds_read_b128 v[224:227], v161 offset:39936
	global_load_lds_dwordx4 v128, s[40:41]
	s_mov_b32 m0, s28
	s_nop 0
	global_load_lds_dwordx4 v132, s[40:41]
	s_waitcnt vmcnt(8)
	s_waitcnt lgkmcnt(0)
	s_nop 0
	s_barrier
	s_setprio 1
	s_waitcnt lgkmcnt(0)
	v_mfma_f32_16x16x32_bf16 v[124:127], v[152:155], v[192:195], v[124:127]
	v_mfma_f32_16x16x32_bf16 v[120:123], v[168:171], v[192:195], v[120:123]
	v_mfma_f32_16x16x32_bf16 v[108:111], v[152:155], v[200:203], v[108:111]
	v_mfma_f32_16x16x32_bf16 v[104:107], v[168:171], v[200:203], v[104:107]
	v_mfma_f32_16x16x32_bf16 v[92:95], v[152:155], v[212:215], v[92:95]
	v_mfma_f32_16x16x32_bf16 v[88:91], v[168:171], v[212:215], v[88:91]
	v_mfma_f32_16x16x32_bf16 v[76:79], v[152:155], v[220:223], v[76:79]
	v_mfma_f32_16x16x32_bf16 v[72:75], v[168:171], v[220:223], v[72:75]
	v_mfma_f32_16x16x32_bf16 v[124:127], v[164:167], v[196:199], v[124:127]
	v_mfma_f32_16x16x32_bf16 v[120:123], v[172:175], v[196:199], v[120:123]
	v_mfma_f32_16x16x32_bf16 v[108:111], v[164:167], v[204:207], v[108:111]
	v_mfma_f32_16x16x32_bf16 v[104:107], v[172:175], v[204:207], v[104:107]
	v_mfma_f32_16x16x32_bf16 v[92:95], v[164:167], v[216:219], v[92:95]
	v_mfma_f32_16x16x32_bf16 v[88:91], v[172:175], v[216:219], v[88:91]
	v_mfma_f32_16x16x32_bf16 v[76:79], v[164:167], v[224:227], v[76:79]
	v_mfma_f32_16x16x32_bf16 v[72:75], v[172:175], v[224:227], v[72:75]
	s_setprio 0
	s_setprio 1
	v_mfma_f32_16x16x32_bf16 v[116:119], v[176:179], v[192:195], v[116:119]
	v_mfma_f32_16x16x32_bf16 v[112:115], v[184:187], v[192:195], v[112:115]
	v_mfma_f32_16x16x32_bf16 v[100:103], v[176:179], v[200:203], v[100:103]
	v_mfma_f32_16x16x32_bf16 v[96:99], v[184:187], v[200:203], v[96:99]
	v_mfma_f32_16x16x32_bf16 v[84:87], v[176:179], v[212:215], v[84:87]
	v_mfma_f32_16x16x32_bf16 v[80:83], v[184:187], v[212:215], v[80:83]
	v_mfma_f32_16x16x32_bf16 v[68:71], v[176:179], v[220:223], v[68:71]
	v_mfma_f32_16x16x32_bf16 v[64:67], v[184:187], v[220:223], v[64:67]
	v_mfma_f32_16x16x32_bf16 v[116:119], v[180:183], v[196:199], v[116:119]
	v_mfma_f32_16x16x32_bf16 v[112:115], v[188:191], v[196:199], v[112:115]
	v_mfma_f32_16x16x32_bf16 v[100:103], v[180:183], v[204:207], v[100:103]
	v_mfma_f32_16x16x32_bf16 v[96:99], v[188:191], v[204:207], v[96:99]
	v_mfma_f32_16x16x32_bf16 v[84:87], v[180:183], v[216:219], v[84:87]
	v_mfma_f32_16x16x32_bf16 v[80:83], v[188:191], v[216:219], v[80:83]
	v_mfma_f32_16x16x32_bf16 v[68:71], v[180:183], v[224:227], v[68:71]
	v_mfma_f32_16x16x32_bf16 v[64:67], v[188:191], v[224:227], v[64:67]
	s_setprio 0
	s_barrier
	s_add_i32 s40, s59, s10
	v_lshl_add_u64 v[156:157], v[156:157], 0, s[8:9]
	s_mov_b32 m0, s40
	ds_read_b128 v[192:195], v161 offset:49152
	ds_read_b128 v[196:199], v161 offset:50176
	ds_read_b128 v[200:203], v161 offset:51200
	ds_read_b128 v[204:207], v161 offset:52224
	ds_read_b128 v[212:215], v161 offset:53248
	ds_read_b128 v[216:219], v161 offset:54272
	ds_read_b128 v[220:223], v161 offset:55296
	ds_read_b128 v[224:227], v161 offset:56320
	global_load_lds_dwordx4 v[156:157], off
	s_add_i32 m0, s40, 0x2000
	s_add_u32 s40, s42, 0x18080
	v_lshl_add_u64 v[156:157], v[208:209], 0, s[8:9]
	s_addc_u32 s41, s43, 0
	s_add_i32 s42, s60, s10
	global_load_lds_dwordx4 v[156:157], off
	s_mov_b32 m0, s42
	s_nop 0
	global_load_lds_dwordx4 v130, s[40:41]
	s_add_i32 m0, s42, 0x2000
	s_nop 0
	global_load_lds_dwordx4 v134, s[40:41]
	v_lshl_add_u64 v[156:157], v[228:229], 0, s[8:9]
	s_mov_b32 m0, s33
	s_nop 0
	global_load_lds_dwordx4 v[156:157], off
	v_lshl_add_u64 v[156:157], v[230:231], 0, s[8:9]
	s_mov_b32 m0, s46
	s_nop 0
	global_load_lds_dwordx4 v[156:157], off
	s_waitcnt vmcnt(8)
	s_waitcnt lgkmcnt(0)
	s_barrier
	s_setprio 1
	s_waitcnt lgkmcnt(0)
	v_mfma_f32_16x16x32_bf16 v[60:63], v[152:155], v[192:195], v[60:63]
	v_mfma_f32_16x16x32_bf16 v[56:59], v[168:171], v[192:195], v[56:59]
	v_mfma_f32_16x16x32_bf16 v[44:47], v[152:155], v[200:203], v[44:47]
	v_mfma_f32_16x16x32_bf16 v[40:43], v[168:171], v[200:203], v[40:43]
	v_mfma_f32_16x16x32_bf16 v[28:31], v[152:155], v[212:215], v[28:31]
	v_mfma_f32_16x16x32_bf16 v[24:27], v[168:171], v[212:215], v[24:27]
	v_mfma_f32_16x16x32_bf16 v[12:15], v[152:155], v[220:223], v[12:15]
	v_mfma_f32_16x16x32_bf16 v[8:11], v[168:171], v[220:223], v[8:11]
	v_mfma_f32_16x16x32_bf16 v[60:63], v[164:167], v[196:199], v[60:63]
	v_mfma_f32_16x16x32_bf16 v[56:59], v[172:175], v[196:199], v[56:59]
	v_mfma_f32_16x16x32_bf16 v[44:47], v[164:167], v[204:207], v[44:47]
	v_mfma_f32_16x16x32_bf16 v[40:43], v[172:175], v[204:207], v[40:43]
	v_mfma_f32_16x16x32_bf16 v[28:31], v[164:167], v[216:219], v[28:31]
	v_mfma_f32_16x16x32_bf16 v[24:27], v[172:175], v[216:219], v[24:27]
	v_mfma_f32_16x16x32_bf16 v[12:15], v[164:167], v[224:227], v[12:15]
	v_mfma_f32_16x16x32_bf16 v[8:11], v[172:175], v[224:227], v[8:11]
	s_setprio 0
	s_setprio 1
	v_mfma_f32_16x16x32_bf16 v[52:55], v[176:179], v[192:195], v[52:55]
	v_mfma_f32_16x16x32_bf16 v[48:51], v[184:187], v[192:195], v[48:51]
	v_mfma_f32_16x16x32_bf16 v[36:39], v[176:179], v[200:203], v[36:39]
	v_mfma_f32_16x16x32_bf16 v[32:35], v[184:187], v[200:203], v[32:35]
	v_mfma_f32_16x16x32_bf16 v[20:23], v[176:179], v[212:215], v[20:23]
	v_mfma_f32_16x16x32_bf16 v[16:19], v[184:187], v[212:215], v[16:19]
	v_mfma_f32_16x16x32_bf16 v[4:7], v[176:179], v[220:223], v[4:7]
	v_mfma_f32_16x16x32_bf16 v[0:3], v[184:187], v[220:223], v[0:3]
	v_mfma_f32_16x16x32_bf16 v[52:55], v[180:183], v[196:199], v[52:55]
	v_mfma_f32_16x16x32_bf16 v[48:51], v[188:191], v[196:199], v[48:51]
	v_mfma_f32_16x16x32_bf16 v[36:39], v[180:183], v[204:207], v[36:39]
	v_mfma_f32_16x16x32_bf16 v[32:35], v[188:191], v[204:207], v[32:35]
	v_mfma_f32_16x16x32_bf16 v[20:23], v[180:183], v[216:219], v[20:23]
	v_mfma_f32_16x16x32_bf16 v[16:19], v[188:191], v[216:219], v[16:19]
	v_mfma_f32_16x16x32_bf16 v[4:7], v[180:183], v[224:227], v[4:7]
	v_mfma_f32_16x16x32_bf16 v[0:3], v[188:191], v[224:227], v[0:3]
	s_setprio 0
	s_barrier
	s_add_i32 s58, s58, 2
	s_add_u32 s56, s56, 0x100
	s_addc_u32 s57, s57, 0
	s_cmp_gt_u32 s58, 3
	s_mov_b64 s[40:41], s[4:5]
	s_cbranch_scc0 .LBB0_862
	s_and_b64 vcc, exec, s[20:21]
	s_cbranch_vccz .LBB0_865
	s_barrier

.LBB0_894:
	s_add_u32 s46, s34, s40
	s_addc_u32 s47, s35, s41
	s_add_u32 s44, s46, 0x100
	s_addc_u32 s45, s47, 0
	s_and_b64 s[42:43], s[38:39], exec
	s_cselect_b32 s43, s19, s45
	s_cselect_b32 s42, s53, s44
	s_add_u32 s40, s30, s40
	s_addc_u32 s41, s31, s41
	s_add_u32 s40, s40, 0x100
	s_addc_u32 s41, s41, 0
	s_and_b64 s[38:39], s[38:39], exec
	s_cselect_b32 s45, s9, s41
	s_cselect_b32 s44, s54, s40
	s_add_u32 s48, s46, 0x10080
	ds_read_b128 v[144:147], v150
	ds_read_b128 v[154:157], v150 offset:1024
	ds_read_b128 v[158:161], v150 offset:2048
	ds_read_b128 v[162:165], v150 offset:3072
	ds_read_b128 v[166:169], v151
	ds_read_b128 v[170:173], v151 offset:1024
	ds_read_b128 v[174:177], v151 offset:2048
	ds_read_b128 v[178:181], v151 offset:3072
	s_addc_u32 s49, s47, 0
	s_add_i32 s64, s50, s10
	s_add_i32 m0, s11, 0xc000
	s_add_i32 s65, s11, 0xe000
	s_add_i32 s61, s64, 0x2000
	s_add_u32 s46, s44, 0x10000
	s_addc_u32 s47, s45, 0
	s_add_i32 s63, s51, s10
	s_add_i32 s62, s63, 0x2000
	s_add_i32 s60, 0, 0x18000
	s_add_i32 s59, 0, 0x1c000
	s_add_u32 s40, s42, 0x10000
	s_addc_u32 s41, s43, 0
	s_add_i32 s58, s60, s10
	s_add_i32 s56, s58, 0x2000
	s_add_u32 s38, s44, 0x10080
	s_addc_u32 s39, s45, 0
	s_add_i32 s57, s59, s10
	s_add_i32 s55, s57, 0x2000
	ds_read_b128 v[182:185], v152
	ds_read_b128 v[186:189], v152 offset:1024
	ds_read_b128 v[190:193], v152 offset:2048
	ds_read_b128 v[194:197], v152 offset:3072
	ds_read_b128 v[198:201], v152 offset:4096
	ds_read_b128 v[202:205], v152 offset:5120
	ds_read_b128 v[206:209], v152 offset:6144
	ds_read_b128 v[212:215], v152 offset:7168
	global_load_lds_dwordx4 v134, s[48:49]
	s_mov_b32 m0, s65
	s_nop 0
	global_load_lds_dwordx4 v130, s[48:49]
	s_waitcnt vmcnt(8)
	s_waitcnt lgkmcnt(0)
	s_nop 0
	s_barrier
	s_setprio 1
	s_waitcnt lgkmcnt(0)
	v_mfma_f32_16x16x32_bf16 v[124:127], v[144:147], v[182:185], v[124:127]
	v_mfma_f32_16x16x32_bf16 v[120:123], v[158:161], v[182:185], v[120:123]
	v_mfma_f32_16x16x32_bf16 v[108:111], v[144:147], v[190:193], v[108:111]
	v_mfma_f32_16x16x32_bf16 v[104:107], v[158:161], v[190:193], v[104:107]
	v_mfma_f32_16x16x32_bf16 v[92:95], v[144:147], v[198:201], v[92:95]
	v_mfma_f32_16x16x32_bf16 v[88:91], v[158:161], v[198:201], v[88:91]
	v_mfma_f32_16x16x32_bf16 v[76:79], v[144:147], v[206:209], v[76:79]
	v_mfma_f32_16x16x32_bf16 v[72:75], v[158:161], v[206:209], v[72:75]
	v_mfma_f32_16x16x32_bf16 v[124:127], v[154:157], v[186:189], v[124:127]
	v_mfma_f32_16x16x32_bf16 v[120:123], v[162:165], v[186:189], v[120:123]
	v_mfma_f32_16x16x32_bf16 v[108:111], v[154:157], v[194:197], v[108:111]
	v_mfma_f32_16x16x32_bf16 v[104:107], v[162:165], v[194:197], v[104:107]
	v_mfma_f32_16x16x32_bf16 v[92:95], v[154:157], v[202:205], v[92:95]
	v_mfma_f32_16x16x32_bf16 v[88:91], v[162:165], v[202:205], v[88:91]
	v_mfma_f32_16x16x32_bf16 v[76:79], v[154:157], v[212:215], v[76:79]
	v_mfma_f32_16x16x32_bf16 v[72:75], v[162:165], v[212:215], v[72:75]
	s_setprio 0
	s_setprio 1
	v_mfma_f32_16x16x32_bf16 v[116:119], v[166:169], v[182:185], v[116:119]
	v_mfma_f32_16x16x32_bf16 v[112:115], v[174:177], v[182:185], v[112:115]
	v_mfma_f32_16x16x32_bf16 v[100:103], v[166:169], v[190:193], v[100:103]
	v_mfma_f32_16x16x32_bf16 v[96:99], v[174:177], v[190:193], v[96:99]
	v_mfma_f32_16x16x32_bf16 v[84:87], v[166:169], v[198:201], v[84:87]
	v_mfma_f32_16x16x32_bf16 v[80:83], v[174:177], v[198:201], v[80:83]
	v_mfma_f32_16x16x32_bf16 v[68:71], v[166:169], v[206:209], v[68:71]
	v_mfma_f32_16x16x32_bf16 v[64:67], v[174:177], v[206:209], v[64:67]
	v_mfma_f32_16x16x32_bf16 v[116:119], v[170:173], v[186:189], v[116:119]
	v_mfma_f32_16x16x32_bf16 v[112:115], v[178:181], v[186:189], v[112:115]
	v_mfma_f32_16x16x32_bf16 v[100:103], v[170:173], v[194:197], v[100:103]
	v_mfma_f32_16x16x32_bf16 v[96:99], v[178:181], v[194:197], v[96:99]
	v_mfma_f32_16x16x32_bf16 v[84:87], v[170:173], v[202:205], v[84:87]
	v_mfma_f32_16x16x32_bf16 v[80:83], v[178:181], v[202:205], v[80:83]
	v_mfma_f32_16x16x32_bf16 v[68:71], v[170:173], v[212:215], v[68:71]
	v_mfma_f32_16x16x32_bf16 v[64:67], v[178:181], v[212:215], v[64:67]
	s_setprio 0
	s_barrier
	s_mov_b32 m0, s64
	v_lshl_add_u64 v[216:217], s[44:45], 0, v[132:133]
	ds_read_b128 v[182:185], v152 offset:16384
	ds_read_b128 v[186:189], v152 offset:17408
	ds_read_b128 v[190:193], v152 offset:18432
	ds_read_b128 v[194:197], v152 offset:19456
	ds_read_b128 v[198:201], v152 offset:20480
	ds_read_b128 v[202:205], v152 offset:21504
	ds_read_b128 v[206:209], v152 offset:22528
	ds_read_b128 v[212:215], v152 offset:23552
	global_load_lds_dwordx4 v[216:217], off
	v_lshl_add_u64 v[218:219], s[44:45], 0, v[128:129]
	s_mov_b32 m0, s61
	s_nop 0
	global_load_lds_dwordx4 v[218:219], off
	s_mov_b32 m0, s63
	v_lshl_add_u64 v[222:223], s[42:43], 0, v[130:131]
	global_load_lds_dwordx4 v132, s[46:47]
	s_mov_b32 m0, s62
	s_nop 0
	global_load_lds_dwordx4 v128, s[46:47]
	v_lshl_add_u64 v[220:221], s[42:43], 0, v[134:135]
	s_mov_b32 m0, s11
	s_nop 0
	global_load_lds_dwordx4 v[220:221], off
	s_mov_b32 m0, s14
	s_nop 0
	global_load_lds_dwordx4 v[222:223], off
	s_waitcnt vmcnt(8)
	s_waitcnt lgkmcnt(0)
	s_nop 0
	s_barrier
	s_setprio 1
	s_waitcnt lgkmcnt(0)
	v_mfma_f32_16x16x32_bf16 v[60:63], v[144:147], v[182:185], v[60:63]
	v_mfma_f32_16x16x32_bf16 v[56:59], v[158:161], v[182:185], v[56:59]
	v_mfma_f32_16x16x32_bf16 v[44:47], v[144:147], v[190:193], v[44:47]
	v_mfma_f32_16x16x32_bf16 v[40:43], v[158:161], v[190:193], v[40:43]
	v_mfma_f32_16x16x32_bf16 v[28:31], v[144:147], v[198:201], v[28:31]
	v_mfma_f32_16x16x32_bf16 v[24:27], v[158:161], v[198:201], v[24:27]
	v_mfma_f32_16x16x32_bf16 v[12:15], v[144:147], v[206:209], v[12:15]
	v_mfma_f32_16x16x32_bf16 v[8:11], v[158:161], v[206:209], v[8:11]
	v_mfma_f32_16x16x32_bf16 v[60:63], v[154:157], v[186:189], v[60:63]
	v_mfma_f32_16x16x32_bf16 v[56:59], v[162:165], v[186:189], v[56:59]
	v_mfma_f32_16x16x32_bf16 v[44:47], v[154:157], v[194:197], v[44:47]
	v_mfma_f32_16x16x32_bf16 v[40:43], v[162:165], v[194:197], v[40:43]
	v_mfma_f32_16x16x32_bf16 v[28:31], v[154:157], v[202:205], v[28:31]
	v_mfma_f32_16x16x32_bf16 v[24:27], v[162:165], v[202:205], v[24:27]
	v_mfma_f32_16x16x32_bf16 v[12:15], v[154:157], v[212:215], v[12:15]
	v_mfma_f32_16x16x32_bf16 v[8:11], v[162:165], v[212:215], v[8:11]
	s_setprio 0
	s_setprio 1
	v_mfma_f32_16x16x32_bf16 v[52:55], v[166:169], v[182:185], v[52:55]
	v_mfma_f32_16x16x32_bf16 v[48:51], v[174:177], v[182:185], v[48:51]
	v_mfma_f32_16x16x32_bf16 v[36:39], v[166:169], v[190:193], v[36:39]
	v_mfma_f32_16x16x32_bf16 v[32:35], v[174:177], v[190:193], v[32:35]
	v_mfma_f32_16x16x32_bf16 v[20:23], v[166:169], v[198:201], v[20:23]
	v_mfma_f32_16x16x32_bf16 v[16:19], v[174:177], v[198:201], v[16:19]
	v_mfma_f32_16x16x32_bf16 v[4:7], v[166:169], v[206:209], v[4:7]
	v_mfma_f32_16x16x32_bf16 v[0:3], v[174:177], v[206:209], v[0:3]
	v_mfma_f32_16x16x32_bf16 v[52:55], v[170:173], v[186:189], v[52:55]
	v_mfma_f32_16x16x32_bf16 v[48:51], v[178:181], v[186:189], v[48:51]
	v_mfma_f32_16x16x32_bf16 v[36:39], v[170:173], v[194:197], v[36:39]
	v_mfma_f32_16x16x32_bf16 v[32:35], v[178:181], v[194:197], v[32:35]
	v_mfma_f32_16x16x32_bf16 v[20:23], v[170:173], v[202:205], v[20:23]
	v_mfma_f32_16x16x32_bf16 v[16:19], v[178:181], v[202:205], v[16:19]
	v_mfma_f32_16x16x32_bf16 v[4:7], v[170:173], v[212:215], v[4:7]
	v_mfma_f32_16x16x32_bf16 v[0:3], v[178:181], v[212:215], v[0:3]
	s_setprio 0
	s_barrier
	v_add_u32_e32 v162, s60, v149
	v_add_u32_e32 v178, s59, v149
	ds_read_b128 v[144:147], v162
	ds_read_b128 v[154:157], v162 offset:1024
	ds_read_b128 v[158:161], v162 offset:2048
	ds_read_b128 v[162:165], v162 offset:3072
	ds_read_b128 v[166:169], v178
	ds_read_b128 v[170:173], v178 offset:1024
	ds_read_b128 v[174:177], v178 offset:2048
	ds_read_b128 v[178:181], v178 offset:3072
	s_mov_b32 m0, s15
	ds_read_b128 v[182:185], v152 offset:32768
	ds_read_b128 v[186:189], v152 offset:33792
	ds_read_b128 v[190:193], v152 offset:34816
	ds_read_b128 v[194:197], v152 offset:35840
	ds_read_b128 v[198:201], v152 offset:36864
	ds_read_b128 v[202:205], v152 offset:37888
	ds_read_b128 v[206:209], v152 offset:38912
	ds_read_b128 v[212:215], v152 offset:39936
	global_load_lds_dwordx4 v134, s[40:41]
	s_mov_b32 m0, s27
	s_nop 0
	global_load_lds_dwordx4 v130, s[40:41]
	s_waitcnt vmcnt(8)
	s_waitcnt lgkmcnt(0)
	s_barrier
	s_setprio 1
	s_waitcnt lgkmcnt(0)
	v_mfma_f32_16x16x32_bf16 v[124:127], v[144:147], v[182:185], v[124:127]
	v_mfma_f32_16x16x32_bf16 v[120:123], v[158:161], v[182:185], v[120:123]
	v_mfma_f32_16x16x32_bf16 v[108:111], v[144:147], v[190:193], v[108:111]
	v_mfma_f32_16x16x32_bf16 v[104:107], v[158:161], v[190:193], v[104:107]
	v_mfma_f32_16x16x32_bf16 v[92:95], v[144:147], v[198:201], v[92:95]
	v_mfma_f32_16x16x32_bf16 v[88:91], v[158:161], v[198:201], v[88:91]
	v_mfma_f32_16x16x32_bf16 v[76:79], v[144:147], v[206:209], v[76:79]
	v_mfma_f32_16x16x32_bf16 v[72:75], v[158:161], v[206:209], v[72:75]
	v_mfma_f32_16x16x32_bf16 v[124:127], v[154:157], v[186:189], v[124:127]
	v_mfma_f32_16x16x32_bf16 v[120:123], v[162:165], v[186:189], v[120:123]
	v_mfma_f32_16x16x32_bf16 v[108:111], v[154:157], v[194:197], v[108:111]
	v_mfma_f32_16x16x32_bf16 v[104:107], v[162:165], v[194:197], v[104:107]
	v_mfma_f32_16x16x32_bf16 v[92:95], v[154:157], v[202:205], v[92:95]
	v_mfma_f32_16x16x32_bf16 v[88:91], v[162:165], v[202:205], v[88:91]
	v_mfma_f32_16x16x32_bf16 v[76:79], v[154:157], v[212:215], v[76:79]
	v_mfma_f32_16x16x32_bf16 v[72:75], v[162:165], v[212:215], v[72:75]
	s_setprio 0
	s_setprio 1
	v_mfma_f32_16x16x32_bf16 v[116:119], v[166:169], v[182:185], v[116:119]
	v_mfma_f32_16x16x32_bf16 v[112:115], v[174:177], v[182:185], v[112:115]
	v_mfma_f32_16x16x32_bf16 v[100:103], v[166:169], v[190:193], v[100:103]
	v_mfma_f32_16x16x32_bf16 v[96:99], v[174:177], v[190:193], v[96:99]
	v_mfma_f32_16x16x32_bf16 v[84:87], v[166:169], v[198:201], v[84:87]
	v_mfma_f32_16x16x32_bf16 v[80:83], v[174:177], v[198:201], v[80:83]
	v_mfma_f32_16x16x32_bf16 v[68:71], v[166:169], v[206:209], v[68:71]
	v_mfma_f32_16x16x32_bf16 v[64:67], v[174:177], v[206:209], v[64:67]
	v_mfma_f32_16x16x32_bf16 v[116:119], v[170:173], v[186:189], v[116:119]
	v_mfma_f32_16x16x32_bf16 v[112:115], v[178:181], v[186:189], v[112:115]
	v_mfma_f32_16x16x32_bf16 v[100:103], v[170:173], v[194:197], v[100:103]
	v_mfma_f32_16x16x32_bf16 v[96:99], v[178:181], v[194:197], v[96:99]
	v_mfma_f32_16x16x32_bf16 v[84:87], v[170:173], v[202:205], v[84:87]
	v_mfma_f32_16x16x32_bf16 v[80:83], v[178:181], v[202:205], v[80:83]
	v_mfma_f32_16x16x32_bf16 v[68:71], v[170:173], v[212:215], v[68:71]
	v_mfma_f32_16x16x32_bf16 v[64:67], v[178:181], v[212:215], v[64:67]
	s_setprio 0
	s_barrier
	s_mov_b32 m0, s58
	v_lshl_add_u64 v[216:217], v[216:217], 0, s[2:3]
	ds_read_b128 v[182:185], v152 offset:49152
	ds_read_b128 v[186:189], v152 offset:50176
	ds_read_b128 v[190:193], v152 offset:51200
	ds_read_b128 v[194:197], v152 offset:52224
	ds_read_b128 v[198:201], v152 offset:53248
	ds_read_b128 v[202:205], v152 offset:54272
	ds_read_b128 v[206:209], v152 offset:55296
	ds_read_b128 v[212:215], v152 offset:56320
	global_load_lds_dwordx4 v[216:217], off
	v_lshl_add_u64 v[216:217], v[218:219], 0, s[2:3]
	s_mov_b32 m0, s56
	s_nop 0
	global_load_lds_dwordx4 v[216:217], off
	s_mov_b32 m0, s57
	s_nop 0
	global_load_lds_dwordx4 v132, s[38:39]
	s_mov_b32 m0, s55
	s_nop 0
	global_load_lds_dwordx4 v128, s[38:39]
	v_lshl_add_u64 v[216:217], v[220:221], 0, s[2:3]
	s_mov_b32 m0, s29
	s_nop 0
	global_load_lds_dwordx4 v[216:217], off
	v_lshl_add_u64 v[216:217], v[222:223], 0, s[2:3]
	s_mov_b32 m0, s33
	s_nop 0
	global_load_lds_dwordx4 v[216:217], off
	s_waitcnt vmcnt(8)
	s_waitcnt lgkmcnt(0)
	s_barrier
	s_setprio 1
	s_waitcnt lgkmcnt(0)
	v_mfma_f32_16x16x32_bf16 v[60:63], v[144:147], v[182:185], v[60:63]
	v_mfma_f32_16x16x32_bf16 v[56:59], v[158:161], v[182:185], v[56:59]
	v_mfma_f32_16x16x32_bf16 v[44:47], v[144:147], v[190:193], v[44:47]
	v_mfma_f32_16x16x32_bf16 v[40:43], v[158:161], v[190:193], v[40:43]
	v_mfma_f32_16x16x32_bf16 v[28:31], v[144:147], v[198:201], v[28:31]
	v_mfma_f32_16x16x32_bf16 v[24:27], v[158:161], v[198:201], v[24:27]
	v_mfma_f32_16x16x32_bf16 v[12:15], v[144:147], v[206:209], v[12:15]
	v_mfma_f32_16x16x32_bf16 v[8:11], v[158:161], v[206:209], v[8:11]
	v_mfma_f32_16x16x32_bf16 v[60:63], v[154:157], v[186:189], v[60:63]
	v_mfma_f32_16x16x32_bf16 v[56:59], v[162:165], v[186:189], v[56:59]
	v_mfma_f32_16x16x32_bf16 v[44:47], v[154:157], v[194:197], v[44:47]
	v_mfma_f32_16x16x32_bf16 v[40:43], v[162:165], v[194:197], v[40:43]
	v_mfma_f32_16x16x32_bf16 v[28:31], v[154:157], v[202:205], v[28:31]
	v_mfma_f32_16x16x32_bf16 v[24:27], v[162:165], v[202:205], v[24:27]
	v_mfma_f32_16x16x32_bf16 v[12:15], v[154:157], v[212:215], v[12:15]
	v_mfma_f32_16x16x32_bf16 v[8:11], v[162:165], v[212:215], v[8:11]
	s_setprio 0
	s_setprio 1
	v_mfma_f32_16x16x32_bf16 v[52:55], v[166:169], v[182:185], v[52:55]
	v_mfma_f32_16x16x32_bf16 v[48:51], v[174:177], v[182:185], v[48:51]
	v_mfma_f32_16x16x32_bf16 v[36:39], v[166:169], v[190:193], v[36:39]
	v_mfma_f32_16x16x32_bf16 v[32:35], v[174:177], v[190:193], v[32:35]
	v_mfma_f32_16x16x32_bf16 v[20:23], v[166:169], v[198:201], v[20:23]
	v_mfma_f32_16x16x32_bf16 v[16:19], v[174:177], v[198:201], v[16:19]
	v_mfma_f32_16x16x32_bf16 v[4:7], v[166:169], v[206:209], v[4:7]
	v_mfma_f32_16x16x32_bf16 v[0:3], v[174:177], v[206:209], v[0:3]
	v_mfma_f32_16x16x32_bf16 v[52:55], v[170:173], v[186:189], v[52:55]
	v_mfma_f32_16x16x32_bf16 v[48:51], v[178:181], v[186:189], v[48:51]
	v_mfma_f32_16x16x32_bf16 v[36:39], v[170:173], v[194:197], v[36:39]
	v_mfma_f32_16x16x32_bf16 v[32:35], v[178:181], v[194:197], v[32:35]
	v_mfma_f32_16x16x32_bf16 v[20:23], v[170:173], v[202:205], v[20:23]
	v_mfma_f32_16x16x32_bf16 v[16:19], v[178:181], v[202:205], v[16:19]
	v_mfma_f32_16x16x32_bf16 v[4:7], v[170:173], v[212:215], v[4:7]
	v_mfma_f32_16x16x32_bf16 v[0:3], v[178:181], v[212:215], v[0:3]
	s_setprio 0
	s_barrier
	s_andn2_b64 vcc, exec, s[36:37]
	s_mov_b64 s[38:39], -1
	s_mov_b64 s[36:37], 0
	s_mov_b64 s[40:41], 0x100
	s_cbranch_vccz .LBB0_894
	s_and_b64 vcc, exec, s[6:7]
	s_cbranch_vccz .LBB0_897
	s_barrier

.LBB0_1155:
	v_add_u32_e32 v1, s46, v193
	ds_read_b128 v[72:75], v1
	ds_read_b128 v[76:79], v1 offset:1024
	ds_read_b128 v[84:87], v1 offset:2048
	ds_read_b128 v[188:191], v1 offset:3072
	v_add_u32_e32 v1, s47, v193
	s_add_u32 s34, s28, s30
	ds_read_b128 v[198:201], v1
	ds_read_b128 v[202:205], v1 offset:1024
	ds_read_b128 v[206:209], v1 offset:2048
	ds_read_b128 v[210:213], v1 offset:3072
	s_addc_u32 s35, s29, s31
	s_add_u32 s34, s34, 0x100
	s_addc_u32 s35, s35, 0
	s_add_u32 s53, s50, s30
	s_addc_u32 s54, s51, s31
	s_cmpk_eq_i32 s30, 0x700
	s_cselect_b32 s37, s21, s35
	s_cselect_b32 s36, s27, s34
	s_cselect_b32 s35, s19, s54
	s_cselect_b32 s34, s49, s53
	v_lshl_add_u64 v[2:3], v[112:113], 0, s[30:31]
	s_add_i32 m0, s38, 0xc000
	ds_read_b128 v[216:219], v197
	ds_read_b128 v[220:223], v197 offset:1024
	ds_read_b128 v[224:227], v197 offset:2048
	ds_read_b128 v[228:231], v197 offset:3072
	ds_read_b128 v[232:235], v197 offset:4096
	ds_read_b128 v[236:239], v197 offset:5120
	ds_read_b128 v[240:243], v197 offset:6144
	ds_read_b128 v[244:247], v197 offset:7168
	global_load_lds_dwordx4 v[2:3], off
	v_lshl_add_u64 v[2:3], v[114:115], 0, s[30:31]
	s_add_i32 m0, s38, 0xe000
	s_nop 0
	global_load_lds_dwordx4 v[2:3], off
	s_waitcnt vmcnt(8)
	s_waitcnt lgkmcnt(0)
	s_nop 0
	s_barrier
	s_setprio 1
	s_waitcnt lgkmcnt(0)
	v_mfma_f32_16x16x32_bf16 v[156:159], v[72:75], v[216:219], v[156:159]
	v_mfma_f32_16x16x32_bf16 v[160:163], v[84:87], v[216:219], v[160:163]
	v_mfma_f32_16x16x32_bf16 v[144:147], v[72:75], v[224:227], v[144:147]
	v_mfma_f32_16x16x32_bf16 v[140:143], v[84:87], v[224:227], v[140:143]
	v_mfma_f32_16x16x32_bf16 v[128:131], v[72:75], v[232:235], v[128:131]
	v_mfma_f32_16x16x32_bf16 v[124:127], v[84:87], v[232:235], v[124:127]
	v_mfma_f32_16x16x32_bf16 v[96:99], v[72:75], v[240:243], v[96:99]
	v_mfma_f32_16x16x32_bf16 v[92:95], v[84:87], v[240:243], v[92:95]
	v_mfma_f32_16x16x32_bf16 v[156:159], v[76:79], v[220:223], v[156:159]
	v_mfma_f32_16x16x32_bf16 v[160:163], v[188:191], v[220:223], v[160:163]
	v_mfma_f32_16x16x32_bf16 v[144:147], v[76:79], v[228:231], v[144:147]
	v_mfma_f32_16x16x32_bf16 v[140:143], v[188:191], v[228:231], v[140:143]
	v_mfma_f32_16x16x32_bf16 v[128:131], v[76:79], v[236:239], v[128:131]
	v_mfma_f32_16x16x32_bf16 v[124:127], v[188:191], v[236:239], v[124:127]
	v_mfma_f32_16x16x32_bf16 v[96:99], v[76:79], v[244:247], v[96:99]
	v_mfma_f32_16x16x32_bf16 v[92:95], v[188:191], v[244:247], v[92:95]
	s_setprio 0
	s_setprio 1
	v_mfma_f32_16x16x32_bf16 v[152:155], v[198:201], v[216:219], v[152:155]
	v_mfma_f32_16x16x32_bf16 v[148:151], v[206:209], v[216:219], v[148:151]
	v_mfma_f32_16x16x32_bf16 v[136:139], v[198:201], v[224:227], v[136:139]
	v_mfma_f32_16x16x32_bf16 v[132:135], v[206:209], v[224:227], v[132:135]
	v_mfma_f32_16x16x32_bf16 v[120:123], v[198:201], v[232:235], v[120:123]
	v_mfma_f32_16x16x32_bf16 v[116:119], v[206:209], v[232:235], v[116:119]
	v_mfma_f32_16x16x32_bf16 v[80:83], v[198:201], v[240:243], v[80:83]
	v_mfma_f32_16x16x32_bf16 v[68:71], v[206:209], v[240:243], v[68:71]
	v_mfma_f32_16x16x32_bf16 v[152:155], v[202:205], v[220:223], v[152:155]
	v_mfma_f32_16x16x32_bf16 v[148:151], v[210:213], v[220:223], v[148:151]
	v_mfma_f32_16x16x32_bf16 v[136:139], v[202:205], v[228:231], v[136:139]
	v_mfma_f32_16x16x32_bf16 v[132:135], v[210:213], v[228:231], v[132:135]
	v_mfma_f32_16x16x32_bf16 v[120:123], v[202:205], v[236:239], v[120:123]
	v_mfma_f32_16x16x32_bf16 v[116:119], v[210:213], v[236:239], v[116:119]
	v_mfma_f32_16x16x32_bf16 v[80:83], v[202:205], v[244:247], v[80:83]
	v_mfma_f32_16x16x32_bf16 v[68:71], v[210:213], v[244:247], v[68:71]
	s_setprio 0
	s_barrier
	s_add_i32 s53, s46, s33
	v_lshl_add_u64 v[248:249], s[34:35], 0, v[166:167]
	s_mov_b32 m0, s53
	ds_read_b128 v[216:219], v197 offset:16384
	ds_read_b128 v[220:223], v197 offset:17408
	ds_read_b128 v[224:227], v197 offset:18432
	ds_read_b128 v[228:231], v197 offset:19456
	ds_read_b128 v[232:235], v197 offset:20480
	ds_read_b128 v[236:239], v197 offset:21504
	ds_read_b128 v[240:243], v197 offset:22528
	ds_read_b128 v[244:247], v197 offset:23552
	global_load_lds_dwordx4 v[248:249], off
	s_add_i32 m0, s53, 0x2000
	s_add_u32 s54, s34, 0x40000
	v_lshl_add_u64 v[250:251], s[34:35], 0, v[170:171]
	s_addc_u32 s55, s35, 0
	s_add_i32 s53, s47, s33
	global_load_lds_dwordx4 v[250:251], off
	s_mov_b32 m0, s53
	v_lshl_add_u64 v[252:253], s[36:37], 0, v[164:165]
	global_load_lds_dwordx4 v166, s[54:55]
	s_add_i32 m0, s53, 0x2000
	v_lshl_add_u64 v[176:177], s[36:37], 0, v[168:169]
	global_load_lds_dwordx4 v170, s[54:55]
	s_mov_b32 m0, s38
	s_nop 0
	global_load_lds_dwordx4 v[252:253], off
	s_mov_b32 m0, s39
	s_nop 0
	global_load_lds_dwordx4 v[176:177], off
	s_waitcnt vmcnt(8)
	s_waitcnt lgkmcnt(0)
	s_barrier
	s_setprio 1
	s_waitcnt lgkmcnt(0)
	v_mfma_f32_16x16x32_bf16 v[64:67], v[72:75], v[216:219], v[64:67]
	v_mfma_f32_16x16x32_bf16 v[60:63], v[84:87], v[216:219], v[60:63]
	v_mfma_f32_16x16x32_bf16 v[48:51], v[72:75], v[224:227], v[48:51]
	v_mfma_f32_16x16x32_bf16 v[44:47], v[84:87], v[224:227], v[44:47]
	v_mfma_f32_16x16x32_bf16 v[32:35], v[72:75], v[232:235], v[32:35]
	v_mfma_f32_16x16x32_bf16 v[28:31], v[84:87], v[232:235], v[28:31]
	v_mfma_f32_16x16x32_bf16 v[16:19], v[72:75], v[240:243], v[16:19]
	v_mfma_f32_16x16x32_bf16 v[12:15], v[84:87], v[240:243], v[12:15]
	v_mfma_f32_16x16x32_bf16 v[64:67], v[76:79], v[220:223], v[64:67]
	v_mfma_f32_16x16x32_bf16 v[60:63], v[188:191], v[220:223], v[60:63]
	v_mfma_f32_16x16x32_bf16 v[48:51], v[76:79], v[228:231], v[48:51]
	v_mfma_f32_16x16x32_bf16 v[44:47], v[188:191], v[228:231], v[44:47]
	v_mfma_f32_16x16x32_bf16 v[32:35], v[76:79], v[236:239], v[32:35]
	v_mfma_f32_16x16x32_bf16 v[28:31], v[188:191], v[236:239], v[28:31]
	v_mfma_f32_16x16x32_bf16 v[16:19], v[76:79], v[244:247], v[16:19]
	v_mfma_f32_16x16x32_bf16 v[12:15], v[188:191], v[244:247], v[12:15]
	s_setprio 0
	s_setprio 1
	v_mfma_f32_16x16x32_bf16 v[56:59], v[198:201], v[216:219], v[56:59]
	v_mfma_f32_16x16x32_bf16 v[52:55], v[206:209], v[216:219], v[52:55]
	v_mfma_f32_16x16x32_bf16 v[40:43], v[198:201], v[224:227], v[40:43]
	v_mfma_f32_16x16x32_bf16 v[36:39], v[206:209], v[224:227], v[36:39]
	v_mfma_f32_16x16x32_bf16 v[24:27], v[198:201], v[232:235], v[24:27]
	v_mfma_f32_16x16x32_bf16 v[20:23], v[206:209], v[232:235], v[20:23]
	v_mfma_f32_16x16x32_bf16 v[8:11], v[198:201], v[240:243], v[8:11]
	v_mfma_f32_16x16x32_bf16 v[2:5], v[206:209], v[240:243], v[4:7]
	v_mfma_f32_16x16x32_bf16 v[56:59], v[202:205], v[220:223], v[56:59]
	v_mfma_f32_16x16x32_bf16 v[52:55], v[210:213], v[220:223], v[52:55]
	v_mfma_f32_16x16x32_bf16 v[40:43], v[202:205], v[228:231], v[40:43]
	v_mfma_f32_16x16x32_bf16 v[36:39], v[210:213], v[228:231], v[36:39]
	v_mfma_f32_16x16x32_bf16 v[24:27], v[202:205], v[236:239], v[24:27]
	v_mfma_f32_16x16x32_bf16 v[20:23], v[210:213], v[236:239], v[20:23]
	v_mfma_f32_16x16x32_bf16 v[8:11], v[202:205], v[244:247], v[8:11]
	v_mfma_f32_16x16x32_bf16 v[2:5], v[210:213], v[244:247], v[2:5]
	s_setprio 0
	s_barrier
	s_add_i32 s53, 0, 0x18000
	v_add_u32_e32 v1, s53, v193
	s_add_i32 s54, 0, 0x1c000
	ds_read_b128 v[72:75], v1
	ds_read_b128 v[76:79], v1 offset:1024
	ds_read_b128 v[84:87], v1 offset:2048
	ds_read_b128 v[188:191], v1 offset:3072
	v_add_u32_e32 v1, s54, v193
	ds_read_b128 v[198:201], v1
	ds_read_b128 v[202:205], v1 offset:1024
	ds_read_b128 v[206:209], v1 offset:2048
	ds_read_b128 v[210:213], v1 offset:3072
	s_add_u32 s36, s36, 0x40000
	s_addc_u32 s37, s37, 0
	s_mov_b32 m0, s40
	ds_read_b128 v[216:219], v197 offset:32768
	ds_read_b128 v[220:223], v197 offset:33792
	ds_read_b128 v[224:227], v197 offset:34816
	ds_read_b128 v[228:231], v197 offset:35840
	ds_read_b128 v[232:235], v197 offset:36864
	ds_read_b128 v[236:239], v197 offset:37888
	ds_read_b128 v[240:243], v197 offset:38912
	ds_read_b128 v[244:247], v197 offset:39936
	global_load_lds_dwordx4 v164, s[36:37]
	s_mov_b32 m0, s41
	s_nop 0
	global_load_lds_dwordx4 v168, s[36:37]
	s_waitcnt vmcnt(8)
	s_waitcnt lgkmcnt(0)
	s_nop 0
	s_barrier
	s_setprio 1
	s_waitcnt lgkmcnt(0)
	v_mfma_f32_16x16x32_bf16 v[156:159], v[72:75], v[216:219], v[156:159]
	v_mfma_f32_16x16x32_bf16 v[160:163], v[84:87], v[216:219], v[160:163]
	v_mfma_f32_16x16x32_bf16 v[144:147], v[72:75], v[224:227], v[144:147]
	v_mfma_f32_16x16x32_bf16 v[140:143], v[84:87], v[224:227], v[140:143]
	v_mfma_f32_16x16x32_bf16 v[128:131], v[72:75], v[232:235], v[128:131]
	v_mfma_f32_16x16x32_bf16 v[124:127], v[84:87], v[232:235], v[124:127]
	v_mfma_f32_16x16x32_bf16 v[96:99], v[72:75], v[240:243], v[96:99]
	v_mfma_f32_16x16x32_bf16 v[92:95], v[84:87], v[240:243], v[92:95]
	v_mfma_f32_16x16x32_bf16 v[156:159], v[76:79], v[220:223], v[156:159]
	v_mfma_f32_16x16x32_bf16 v[160:163], v[188:191], v[220:223], v[160:163]
	v_mfma_f32_16x16x32_bf16 v[144:147], v[76:79], v[228:231], v[144:147]
	v_mfma_f32_16x16x32_bf16 v[140:143], v[188:191], v[228:231], v[140:143]
	v_mfma_f32_16x16x32_bf16 v[128:131], v[76:79], v[236:239], v[128:131]
	v_mfma_f32_16x16x32_bf16 v[124:127], v[188:191], v[236:239], v[124:127]
	v_mfma_f32_16x16x32_bf16 v[96:99], v[76:79], v[244:247], v[96:99]
	v_mfma_f32_16x16x32_bf16 v[92:95], v[188:191], v[244:247], v[92:95]
	s_setprio 0
	s_setprio 1
	v_mfma_f32_16x16x32_bf16 v[152:155], v[198:201], v[216:219], v[152:155]
	v_mfma_f32_16x16x32_bf16 v[148:151], v[206:209], v[216:219], v[148:151]
	v_mfma_f32_16x16x32_bf16 v[136:139], v[198:201], v[224:227], v[136:139]
	v_mfma_f32_16x16x32_bf16 v[132:135], v[206:209], v[224:227], v[132:135]
	v_mfma_f32_16x16x32_bf16 v[120:123], v[198:201], v[232:235], v[120:123]
	v_mfma_f32_16x16x32_bf16 v[116:119], v[206:209], v[232:235], v[116:119]
	v_mfma_f32_16x16x32_bf16 v[80:83], v[198:201], v[240:243], v[80:83]
	v_mfma_f32_16x16x32_bf16 v[68:71], v[206:209], v[240:243], v[68:71]
	v_mfma_f32_16x16x32_bf16 v[152:155], v[202:205], v[220:223], v[152:155]
	v_mfma_f32_16x16x32_bf16 v[148:151], v[210:213], v[220:223], v[148:151]
	v_mfma_f32_16x16x32_bf16 v[136:139], v[202:205], v[228:231], v[136:139]
	v_mfma_f32_16x16x32_bf16 v[132:135], v[210:213], v[228:231], v[132:135]
	v_mfma_f32_16x16x32_bf16 v[120:123], v[202:205], v[236:239], v[120:123]
	v_mfma_f32_16x16x32_bf16 v[116:119], v[210:213], v[236:239], v[116:119]
	v_mfma_f32_16x16x32_bf16 v[80:83], v[202:205], v[244:247], v[80:83]
	v_mfma_f32_16x16x32_bf16 v[68:71], v[210:213], v[244:247], v[68:71]
	s_setprio 0
	s_barrier
	s_add_i32 s36, s53, s33
	v_lshl_add_u64 v[6:7], v[248:249], 0, s[10:11]
	s_mov_b32 m0, s36
	ds_read_b128 v[216:219], v197 offset:49152
	ds_read_b128 v[220:223], v197 offset:50176
	ds_read_b128 v[224:227], v197 offset:51200
	ds_read_b128 v[228:231], v197 offset:52224
	ds_read_b128 v[232:235], v197 offset:53248
	ds_read_b128 v[236:239], v197 offset:54272
	ds_read_b128 v[240:243], v197 offset:55296
	ds_read_b128 v[244:247], v197 offset:56320
	global_load_lds_dwordx4 v[6:7], off
	s_add_i32 m0, s36, 0x2000
	s_add_u32 s34, s34, 0x40080
	v_lshl_add_u64 v[6:7], v[250:251], 0, s[10:11]
	s_addc_u32 s35, s35, 0
	s_add_i32 s36, s54, s33
	global_load_lds_dwordx4 v[6:7], off
	s_mov_b32 m0, s36
	s_nop 0
	global_load_lds_dwordx4 v166, s[34:35]
	s_add_i32 m0, s36, 0x2000
	s_nop 0
	global_load_lds_dwordx4 v170, s[34:35]
	v_lshl_add_u64 v[6:7], v[252:253], 0, s[10:11]
	s_mov_b32 m0, s43
	s_nop 0
	global_load_lds_dwordx4 v[6:7], off
	v_lshl_add_u64 v[6:7], v[176:177], 0, s[10:11]
	s_mov_b32 m0, s44
	s_nop 0
	global_load_lds_dwordx4 v[6:7], off
	s_waitcnt vmcnt(8)
	s_waitcnt lgkmcnt(0)
	s_barrier
	s_setprio 1
	s_waitcnt lgkmcnt(0)
	v_mfma_f32_16x16x32_bf16 v[64:67], v[72:75], v[216:219], v[64:67]
	v_mfma_f32_16x16x32_bf16 v[60:63], v[84:87], v[216:219], v[60:63]
	v_mfma_f32_16x16x32_bf16 v[48:51], v[72:75], v[224:227], v[48:51]
	v_mfma_f32_16x16x32_bf16 v[44:47], v[84:87], v[224:227], v[44:47]
	v_mfma_f32_16x16x32_bf16 v[32:35], v[72:75], v[232:235], v[32:35]
	v_mfma_f32_16x16x32_bf16 v[28:31], v[84:87], v[232:235], v[28:31]
	v_mfma_f32_16x16x32_bf16 v[16:19], v[72:75], v[240:243], v[16:19]
	v_mfma_f32_16x16x32_bf16 v[12:15], v[84:87], v[240:243], v[12:15]
	v_mfma_f32_16x16x32_bf16 v[64:67], v[76:79], v[220:223], v[64:67]
	v_mfma_f32_16x16x32_bf16 v[60:63], v[188:191], v[220:223], v[60:63]
	v_mfma_f32_16x16x32_bf16 v[48:51], v[76:79], v[228:231], v[48:51]
	v_mfma_f32_16x16x32_bf16 v[44:47], v[188:191], v[228:231], v[44:47]
	v_mfma_f32_16x16x32_bf16 v[32:35], v[76:79], v[236:239], v[32:35]
	v_mfma_f32_16x16x32_bf16 v[28:31], v[188:191], v[236:239], v[28:31]
	v_mfma_f32_16x16x32_bf16 v[16:19], v[76:79], v[244:247], v[16:19]
	v_mfma_f32_16x16x32_bf16 v[12:15], v[188:191], v[244:247], v[12:15]
	s_setprio 0
	s_setprio 1
	v_mfma_f32_16x16x32_bf16 v[56:59], v[198:201], v[216:219], v[56:59]
	v_mfma_f32_16x16x32_bf16 v[52:55], v[206:209], v[216:219], v[52:55]
	v_mfma_f32_16x16x32_bf16 v[40:43], v[198:201], v[224:227], v[40:43]
	v_mfma_f32_16x16x32_bf16 v[36:39], v[206:209], v[224:227], v[36:39]
	v_mfma_f32_16x16x32_bf16 v[24:27], v[198:201], v[232:235], v[24:27]
	v_mfma_f32_16x16x32_bf16 v[20:23], v[206:209], v[232:235], v[20:23]
	v_mfma_f32_16x16x32_bf16 v[6:9], v[198:201], v[240:243], v[8:11]
	v_mfma_f32_16x16x32_bf16 v[2:5], v[206:209], v[240:243], v[2:5]
	v_mfma_f32_16x16x32_bf16 v[56:59], v[202:205], v[220:223], v[56:59]
	v_mfma_f32_16x16x32_bf16 v[52:55], v[210:213], v[220:223], v[52:55]
	v_mfma_f32_16x16x32_bf16 v[40:43], v[202:205], v[228:231], v[40:43]
	v_mfma_f32_16x16x32_bf16 v[36:39], v[210:213], v[228:231], v[36:39]
	v_mfma_f32_16x16x32_bf16 v[24:27], v[202:205], v[236:239], v[24:27]
	v_mfma_f32_16x16x32_bf16 v[20:23], v[210:213], v[236:239], v[20:23]
	v_mfma_f32_16x16x32_bf16 v[8:11], v[202:205], v[244:247], v[6:9]
	v_mfma_f32_16x16x32_bf16 v[4:7], v[210:213], v[244:247], v[2:5]
	s_setprio 0
	s_barrier
	s_add_i32 s52, s52, 2
	s_add_u32 s30, s30, 0x100
	s_addc_u32 s31, s31, 0
	s_cmp_gt_u32 s52, 13
	s_cbranch_scc1 .LBB0_1158

.LBB0_1243:
	ds_read_b128 v[128:131], v183
	ds_read_b128 v[132:135], v183 offset:1024
	ds_read_b128 v[136:139], v183 offset:2048
	ds_read_b128 v[140:143], v183 offset:3072
	ds_read_b128 v[144:147], v184
	ds_read_b128 v[164:167], v184 offset:1024
	ds_read_b128 v[168:171], v184 offset:2048
	ds_read_b128 v[172:175], v184 offset:3072
	s_add_u32 s20, s18, 0xfffc0080
	s_addc_u32 s21, s19, -1
	s_cmp_eq_u32 s44, 12
	s_cselect_b32 s23, s13, s21
	s_cselect_b32 s22, s40, s20
	s_cselect_b32 s21, s11, s43
	s_cselect_b32 s20, s41, s42
	s_add_i32 m0, s25, 0xc000
	ds_read_b128 v[176:179], v185
	ds_read_b128 v[188:191], v185 offset:1024
	ds_read_b128 v[192:195], v185 offset:2048
	ds_read_b128 v[196:199], v185 offset:3072
	ds_read_b128 v[200:203], v185 offset:4096
	ds_read_b128 v[204:207], v185 offset:5120
	ds_read_b128 v[208:211], v185 offset:6144
	ds_read_b128 v[216:219], v185 offset:7168
	global_load_lds_dwordx4 v156, s[18:19]
	s_add_i32 m0, s25, 0xe000
	s_nop 0
	global_load_lds_dwordx4 v158, s[18:19]
	s_waitcnt vmcnt(8)
	s_waitcnt lgkmcnt(0)
	s_nop 0
	s_barrier
	s_setprio 1
	s_waitcnt lgkmcnt(0)
	v_mfma_f32_16x16x32_bf16 v[124:127], v[128:131], v[176:179], v[124:127]
	v_mfma_f32_16x16x32_bf16 v[120:123], v[136:139], v[176:179], v[120:123]
	v_mfma_f32_16x16x32_bf16 v[116:119], v[128:131], v[192:195], v[116:119]
	v_mfma_f32_16x16x32_bf16 v[112:115], v[136:139], v[192:195], v[112:115]
	v_mfma_f32_16x16x32_bf16 v[108:111], v[128:131], v[200:203], v[108:111]
	v_mfma_f32_16x16x32_bf16 v[100:103], v[136:139], v[200:203], v[100:103]
	v_mfma_f32_16x16x32_bf16 v[88:91], v[128:131], v[208:211], v[88:91]
	v_mfma_f32_16x16x32_bf16 v[80:83], v[136:139], v[208:211], v[80:83]
	v_mfma_f32_16x16x32_bf16 v[124:127], v[132:135], v[188:191], v[124:127]
	v_mfma_f32_16x16x32_bf16 v[120:123], v[140:143], v[188:191], v[120:123]
	v_mfma_f32_16x16x32_bf16 v[116:119], v[132:135], v[196:199], v[116:119]
	v_mfma_f32_16x16x32_bf16 v[112:115], v[140:143], v[196:199], v[112:115]
	v_mfma_f32_16x16x32_bf16 v[108:111], v[132:135], v[204:207], v[108:111]
	v_mfma_f32_16x16x32_bf16 v[100:103], v[140:143], v[204:207], v[100:103]
	v_mfma_f32_16x16x32_bf16 v[88:91], v[132:135], v[216:219], v[88:91]
	v_mfma_f32_16x16x32_bf16 v[80:83], v[140:143], v[216:219], v[80:83]
	s_setprio 0
	s_setprio 1
	v_mfma_f32_16x16x32_bf16 v[104:107], v[144:147], v[176:179], v[104:107]
	v_mfma_f32_16x16x32_bf16 v[96:99], v[168:171], v[176:179], v[96:99]
	v_mfma_f32_16x16x32_bf16 v[92:95], v[144:147], v[192:195], v[92:95]
	v_mfma_f32_16x16x32_bf16 v[84:87], v[168:171], v[192:195], v[84:87]
	v_mfma_f32_16x16x32_bf16 v[76:79], v[144:147], v[200:203], v[76:79]
	v_mfma_f32_16x16x32_bf16 v[72:75], v[168:171], v[200:203], v[72:75]
	v_mfma_f32_16x16x32_bf16 v[68:71], v[144:147], v[208:211], v[68:71]
	v_mfma_f32_16x16x32_bf16 v[64:67], v[168:171], v[208:211], v[64:67]
	v_mfma_f32_16x16x32_bf16 v[104:107], v[164:167], v[188:191], v[104:107]
	v_mfma_f32_16x16x32_bf16 v[96:99], v[172:175], v[188:191], v[96:99]
	v_mfma_f32_16x16x32_bf16 v[92:95], v[164:167], v[196:199], v[92:95]
	v_mfma_f32_16x16x32_bf16 v[84:87], v[172:175], v[196:199], v[84:87]
	v_mfma_f32_16x16x32_bf16 v[76:79], v[164:167], v[204:207], v[76:79]
	v_mfma_f32_16x16x32_bf16 v[72:75], v[172:175], v[204:207], v[72:75]
	v_mfma_f32_16x16x32_bf16 v[68:71], v[164:167], v[216:219], v[68:71]
	v_mfma_f32_16x16x32_bf16 v[64:67], v[172:175], v[216:219], v[64:67]
	s_setprio 0
	s_barrier
	s_add_i32 s45, s36, s24
	v_lshl_add_u64 v[212:213], s[20:21], 0, v[152:153]
	s_mov_b32 m0, s45
	ds_read_b128 v[176:179], v185 offset:16384
	ds_read_b128 v[188:191], v185 offset:17408
	ds_read_b128 v[192:195], v185 offset:18432
	ds_read_b128 v[196:199], v185 offset:19456
	ds_read_b128 v[200:203], v185 offset:20480
	ds_read_b128 v[204:207], v185 offset:21504
	ds_read_b128 v[208:211], v185 offset:22528
	ds_read_b128 v[216:219], v185 offset:23552
	global_load_lds_dwordx4 v[212:213], off
	s_add_i32 m0, s45, 0x2000
	s_add_u32 s46, s20, 0x40000
	v_lshl_add_u64 v[220:221], s[20:21], 0, v[148:149]
	s_addc_u32 s47, s21, 0
	s_add_i32 s45, s37, s24
	global_load_lds_dwordx4 v[220:221], off
	s_mov_b32 m0, s45
	v_lshl_add_u64 v[224:225], s[22:23], 0, v[150:151]
	global_load_lds_dwordx4 v152, s[46:47]
	s_add_i32 m0, s45, 0x2000
	s_nop 0
	global_load_lds_dwordx4 v148, s[46:47]
	v_lshl_add_u64 v[222:223], s[22:23], 0, v[154:155]
	s_mov_b32 m0, s25
	s_nop 0
	global_load_lds_dwordx4 v[222:223], off
	s_mov_b32 m0, s26
	s_nop 0
	global_load_lds_dwordx4 v[224:225], off
	s_waitcnt vmcnt(8)
	s_waitcnt lgkmcnt(0)
	s_nop 0
	s_barrier
	s_setprio 1
	s_waitcnt lgkmcnt(0)
	v_mfma_f32_16x16x32_bf16 v[60:63], v[128:131], v[176:179], v[60:63]
	v_mfma_f32_16x16x32_bf16 v[56:59], v[136:139], v[176:179], v[56:59]
	v_mfma_f32_16x16x32_bf16 v[52:55], v[128:131], v[192:195], v[52:55]
	v_mfma_f32_16x16x32_bf16 v[48:51], v[136:139], v[192:195], v[48:51]
	v_mfma_f32_16x16x32_bf16 v[40:43], v[128:131], v[200:203], v[40:43]
	v_mfma_f32_16x16x32_bf16 v[32:35], v[136:139], v[200:203], v[32:35]
	v_mfma_f32_16x16x32_bf16 v[20:23], v[128:131], v[208:211], v[20:23]
	v_mfma_f32_16x16x32_bf16 v[16:19], v[136:139], v[208:211], v[16:19]
	v_mfma_f32_16x16x32_bf16 v[60:63], v[132:135], v[188:191], v[60:63]
	v_mfma_f32_16x16x32_bf16 v[56:59], v[140:143], v[188:191], v[56:59]
	v_mfma_f32_16x16x32_bf16 v[52:55], v[132:135], v[196:199], v[52:55]
	v_mfma_f32_16x16x32_bf16 v[48:51], v[140:143], v[196:199], v[48:51]
	v_mfma_f32_16x16x32_bf16 v[40:43], v[132:135], v[204:207], v[40:43]
	v_mfma_f32_16x16x32_bf16 v[32:35], v[140:143], v[204:207], v[32:35]
	v_mfma_f32_16x16x32_bf16 v[20:23], v[132:135], v[216:219], v[20:23]
	v_mfma_f32_16x16x32_bf16 v[16:19], v[140:143], v[216:219], v[16:19]
	s_setprio 0
	s_setprio 1
	v_mfma_f32_16x16x32_bf16 v[44:47], v[144:147], v[176:179], v[44:47]
	v_mfma_f32_16x16x32_bf16 v[36:39], v[168:171], v[176:179], v[36:39]
	v_mfma_f32_16x16x32_bf16 v[28:31], v[144:147], v[192:195], v[28:31]
	v_mfma_f32_16x16x32_bf16 v[24:27], v[168:171], v[192:195], v[24:27]
	v_mfma_f32_16x16x32_bf16 v[12:15], v[144:147], v[200:203], v[12:15]
	v_mfma_f32_16x16x32_bf16 v[8:11], v[168:171], v[200:203], v[8:11]
	v_mfma_f32_16x16x32_bf16 v[4:7], v[144:147], v[208:211], v[4:7]
	v_mfma_f32_16x16x32_bf16 v[0:3], v[168:171], v[208:211], v[0:3]
	v_mfma_f32_16x16x32_bf16 v[44:47], v[164:167], v[188:191], v[44:47]
	v_mfma_f32_16x16x32_bf16 v[36:39], v[172:175], v[188:191], v[36:39]
	v_mfma_f32_16x16x32_bf16 v[28:31], v[164:167], v[196:199], v[28:31]
	v_mfma_f32_16x16x32_bf16 v[24:27], v[172:175], v[196:199], v[24:27]
	v_mfma_f32_16x16x32_bf16 v[12:15], v[164:167], v[204:207], v[12:15]
	v_mfma_f32_16x16x32_bf16 v[8:11], v[172:175], v[204:207], v[8:11]
	v_mfma_f32_16x16x32_bf16 v[4:7], v[164:167], v[216:219], v[4:7]
	v_mfma_f32_16x16x32_bf16 v[0:3], v[172:175], v[216:219], v[0:3]
	s_setprio 0
	s_barrier
	s_add_i32 s45, 0, 0x18000
	s_add_i32 s46, 0, 0x1c000
	v_add_u32_e32 v140, s45, v181
	v_add_u32_e32 v172, s46, v181
	ds_read_b128 v[128:131], v140
	ds_read_b128 v[132:135], v140 offset:1024
	ds_read_b128 v[136:139], v140 offset:2048
	ds_read_b128 v[140:143], v140 offset:3072
	ds_read_b128 v[144:147], v172
	ds_read_b128 v[164:167], v172 offset:1024
	ds_read_b128 v[168:171], v172 offset:2048
	ds_read_b128 v[172:175], v172 offset:3072
	s_add_u32 s22, s22, 0x40000
	s_addc_u32 s23, s23, 0
	s_mov_b32 m0, s27
	ds_read_b128 v[176:179], v185 offset:32768
	ds_read_b128 v[188:191], v185 offset:33792
	ds_read_b128 v[192:195], v185 offset:34816
	ds_read_b128 v[196:199], v185 offset:35840
	ds_read_b128 v[200:203], v185 offset:36864
	ds_read_b128 v[204:207], v185 offset:37888
	ds_read_b128 v[208:211], v185 offset:38912
	ds_read_b128 v[216:219], v185 offset:39936
	global_load_lds_dwordx4 v154, s[22:23]
	s_mov_b32 m0, s28
	s_nop 0
	global_load_lds_dwordx4 v150, s[22:23]
	s_waitcnt vmcnt(8)
	s_waitcnt lgkmcnt(0)
	s_nop 0
	s_barrier
	s_setprio 1
	s_waitcnt lgkmcnt(0)
	v_mfma_f32_16x16x32_bf16 v[124:127], v[128:131], v[176:179], v[124:127]
	v_mfma_f32_16x16x32_bf16 v[120:123], v[136:139], v[176:179], v[120:123]
	v_mfma_f32_16x16x32_bf16 v[116:119], v[128:131], v[192:195], v[116:119]
	v_mfma_f32_16x16x32_bf16 v[112:115], v[136:139], v[192:195], v[112:115]
	v_mfma_f32_16x16x32_bf16 v[108:111], v[128:131], v[200:203], v[108:111]
	v_mfma_f32_16x16x32_bf16 v[100:103], v[136:139], v[200:203], v[100:103]
	v_mfma_f32_16x16x32_bf16 v[88:91], v[128:131], v[208:211], v[88:91]
	v_mfma_f32_16x16x32_bf16 v[80:83], v[136:139], v[208:211], v[80:83]
	v_mfma_f32_16x16x32_bf16 v[124:127], v[132:135], v[188:191], v[124:127]
	v_mfma_f32_16x16x32_bf16 v[120:123], v[140:143], v[188:191], v[120:123]
	v_mfma_f32_16x16x32_bf16 v[116:119], v[132:135], v[196:199], v[116:119]
	v_mfma_f32_16x16x32_bf16 v[112:115], v[140:143], v[196:199], v[112:115]
	v_mfma_f32_16x16x32_bf16 v[108:111], v[132:135], v[204:207], v[108:111]
	v_mfma_f32_16x16x32_bf16 v[100:103], v[140:143], v[204:207], v[100:103]
	v_mfma_f32_16x16x32_bf16 v[88:91], v[132:135], v[216:219], v[88:91]
	v_mfma_f32_16x16x32_bf16 v[80:83], v[140:143], v[216:219], v[80:83]
	s_setprio 0
	s_setprio 1
	v_mfma_f32_16x16x32_bf16 v[104:107], v[144:147], v[176:179], v[104:107]
	v_mfma_f32_16x16x32_bf16 v[96:99], v[168:171], v[176:179], v[96:99]
	v_mfma_f32_16x16x32_bf16 v[92:95], v[144:147], v[192:195], v[92:95]
	v_mfma_f32_16x16x32_bf16 v[84:87], v[168:171], v[192:195], v[84:87]
	v_mfma_f32_16x16x32_bf16 v[76:79], v[144:147], v[200:203], v[76:79]
	v_mfma_f32_16x16x32_bf16 v[72:75], v[168:171], v[200:203], v[72:75]
	v_mfma_f32_16x16x32_bf16 v[68:71], v[144:147], v[208:211], v[68:71]
	v_mfma_f32_16x16x32_bf16 v[64:67], v[168:171], v[208:211], v[64:67]
	v_mfma_f32_16x16x32_bf16 v[104:107], v[164:167], v[188:191], v[104:107]
	v_mfma_f32_16x16x32_bf16 v[96:99], v[172:175], v[188:191], v[96:99]
	v_mfma_f32_16x16x32_bf16 v[92:95], v[164:167], v[196:199], v[92:95]
	v_mfma_f32_16x16x32_bf16 v[84:87], v[172:175], v[196:199], v[84:87]
	v_mfma_f32_16x16x32_bf16 v[76:79], v[164:167], v[204:207], v[76:79]
	v_mfma_f32_16x16x32_bf16 v[72:75], v[172:175], v[204:207], v[72:75]
	v_mfma_f32_16x16x32_bf16 v[68:71], v[164:167], v[216:219], v[68:71]
	v_mfma_f32_16x16x32_bf16 v[64:67], v[172:175], v[216:219], v[64:67]
	s_setprio 0
	s_barrier
	s_add_i32 s22, s45, s24
	v_lshl_add_u64 v[212:213], v[212:213], 0, s[6:7]
	s_mov_b32 m0, s22
	ds_read_b128 v[176:179], v185 offset:49152
	ds_read_b128 v[188:191], v185 offset:50176
	ds_read_b128 v[192:195], v185 offset:51200
	ds_read_b128 v[196:199], v185 offset:52224
	ds_read_b128 v[200:203], v185 offset:53248
	ds_read_b128 v[204:207], v185 offset:54272
	ds_read_b128 v[208:211], v185 offset:55296
	ds_read_b128 v[216:219], v185 offset:56320
	global_load_lds_dwordx4 v[212:213], off
	s_add_i32 m0, s22, 0x2000
	s_add_u32 s20, s20, 0x40080
	v_lshl_add_u64 v[212:213], v[220:221], 0, s[6:7]
	s_addc_u32 s21, s21, 0
	s_add_i32 s22, s46, s24
	global_load_lds_dwordx4 v[212:213], off
	s_mov_b32 m0, s22
	s_nop 0
	global_load_lds_dwordx4 v152, s[20:21]
	s_add_i32 m0, s22, 0x2000
	s_nop 0
	global_load_lds_dwordx4 v148, s[20:21]
	v_lshl_add_u64 v[212:213], v[222:223], 0, s[6:7]
	s_mov_b32 m0, s33
	s_nop 0
	global_load_lds_dwordx4 v[212:213], off
	v_lshl_add_u64 v[212:213], v[224:225], 0, s[6:7]
	s_mov_b32 m0, s34
	s_nop 0
	global_load_lds_dwordx4 v[212:213], off
	s_waitcnt vmcnt(8)
	s_waitcnt lgkmcnt(0)
	s_barrier
	s_setprio 1
	s_waitcnt lgkmcnt(0)
	v_mfma_f32_16x16x32_bf16 v[60:63], v[128:131], v[176:179], v[60:63]
	v_mfma_f32_16x16x32_bf16 v[56:59], v[136:139], v[176:179], v[56:59]
	v_mfma_f32_16x16x32_bf16 v[52:55], v[128:131], v[192:195], v[52:55]
	v_mfma_f32_16x16x32_bf16 v[48:51], v[136:139], v[192:195], v[48:51]
	v_mfma_f32_16x16x32_bf16 v[40:43], v[128:131], v[200:203], v[40:43]
	v_mfma_f32_16x16x32_bf16 v[32:35], v[136:139], v[200:203], v[32:35]
	v_mfma_f32_16x16x32_bf16 v[20:23], v[128:131], v[208:211], v[20:23]
	v_mfma_f32_16x16x32_bf16 v[16:19], v[136:139], v[208:211], v[16:19]
	v_mfma_f32_16x16x32_bf16 v[60:63], v[132:135], v[188:191], v[60:63]
	v_mfma_f32_16x16x32_bf16 v[56:59], v[140:143], v[188:191], v[56:59]
	v_mfma_f32_16x16x32_bf16 v[52:55], v[132:135], v[196:199], v[52:55]
	v_mfma_f32_16x16x32_bf16 v[48:51], v[140:143], v[196:199], v[48:51]
	v_mfma_f32_16x16x32_bf16 v[40:43], v[132:135], v[204:207], v[40:43]
	v_mfma_f32_16x16x32_bf16 v[32:35], v[140:143], v[204:207], v[32:35]
	v_mfma_f32_16x16x32_bf16 v[20:23], v[132:135], v[216:219], v[20:23]
	v_mfma_f32_16x16x32_bf16 v[16:19], v[140:143], v[216:219], v[16:19]
	s_setprio 0
	s_setprio 1
	v_mfma_f32_16x16x32_bf16 v[44:47], v[144:147], v[176:179], v[44:47]
	v_mfma_f32_16x16x32_bf16 v[36:39], v[168:171], v[176:179], v[36:39]
	v_mfma_f32_16x16x32_bf16 v[28:31], v[144:147], v[192:195], v[28:31]
	v_mfma_f32_16x16x32_bf16 v[24:27], v[168:171], v[192:195], v[24:27]
	v_mfma_f32_16x16x32_bf16 v[12:15], v[144:147], v[200:203], v[12:15]
	v_mfma_f32_16x16x32_bf16 v[8:11], v[168:171], v[200:203], v[8:11]
	v_mfma_f32_16x16x32_bf16 v[4:7], v[144:147], v[208:211], v[4:7]
	v_mfma_f32_16x16x32_bf16 v[0:3], v[168:171], v[208:211], v[0:3]
	v_mfma_f32_16x16x32_bf16 v[44:47], v[164:167], v[188:191], v[44:47]
	v_mfma_f32_16x16x32_bf16 v[36:39], v[172:175], v[188:191], v[36:39]
	v_mfma_f32_16x16x32_bf16 v[28:31], v[164:167], v[196:199], v[28:31]
	v_mfma_f32_16x16x32_bf16 v[24:27], v[172:175], v[196:199], v[24:27]
	v_mfma_f32_16x16x32_bf16 v[12:15], v[164:167], v[204:207], v[12:15]
	v_mfma_f32_16x16x32_bf16 v[8:11], v[172:175], v[204:207], v[8:11]
	v_mfma_f32_16x16x32_bf16 v[4:7], v[164:167], v[216:219], v[4:7]
	v_mfma_f32_16x16x32_bf16 v[0:3], v[172:175], v[216:219], v[0:3]
	s_setprio 0
	s_barrier
	s_add_i32 s44, s44, 2
	s_add_u32 s18, s18, 0x100
	s_addc_u32 s19, s19, 0
	s_add_u32 s42, s42, 0x100
	s_addc_u32 s43, s43, 0
	s_cmp_gt_u32 s44, 13
	s_cbranch_scc0 .LBB0_1243
	s_and_b64 vcc, exec, s[8:9]
	s_cbranch_vccz .LBB0_1246
	s_barrier

.LBB0_1325:
	ds_read_b128 v[120:123], v209
	ds_read_b128 v[128:131], v209 offset:1024
	ds_read_b128 v[136:139], v209 offset:2048
	ds_read_b128 v[140:143], v209 offset:3072
	ds_read_b128 v[144:147], v210
	ds_read_b128 v[148:151], v210 offset:1024
	ds_read_b128 v[152:155], v210 offset:2048
	ds_read_b128 v[156:159], v210 offset:3072
	s_add_u32 s4, s22, 0x100
	s_addc_u32 s5, s23, 0
	s_cmp_eq_u32 s47, 40
	s_cselect_b32 s27, s17, s5
	s_cselect_b32 s26, s16, s4
	s_cselect_b32 s25, s19, s46
	s_cselect_b32 s24, s18, s21
	s_add_i32 m0, s29, 0xc000
	ds_read_b128 v[160:163], v211
	ds_read_b128 v[164:167], v211 offset:1024
	ds_read_b128 v[184:187], v211 offset:2048
	ds_read_b128 v[188:191], v211 offset:3072
	ds_read_b128 v[192:195], v211 offset:4096
	ds_read_b128 v[196:199], v211 offset:5120
	ds_read_b128 v[200:203], v211 offset:6144
	ds_read_b128 v[216:219], v211 offset:7168
	global_load_lds_dwordx4 v176, s[22:23]
	s_add_i32 m0, s29, 0xe000
	s_nop 0
	global_load_lds_dwordx4 v178, s[22:23]
	s_waitcnt vmcnt(8)
	s_waitcnt lgkmcnt(0)
	s_barrier
	s_setprio 1
	s_waitcnt lgkmcnt(0)
	v_mfma_f32_16x16x32_bf16 v[132:135], v[120:123], v[160:163], v[132:135]
	v_mfma_f32_16x16x32_bf16 v[124:127], v[136:139], v[160:163], v[124:127]
	v_mfma_f32_16x16x32_bf16 v[108:111], v[120:123], v[184:187], v[108:111]
	v_mfma_f32_16x16x32_bf16 v[104:107], v[136:139], v[184:187], v[104:107]
	v_mfma_f32_16x16x32_bf16 v[92:95], v[120:123], v[192:195], v[92:95]
	v_mfma_f32_16x16x32_bf16 v[88:91], v[136:139], v[192:195], v[88:91]
	v_mfma_f32_16x16x32_bf16 v[76:79], v[120:123], v[200:203], v[76:79]
	v_mfma_f32_16x16x32_bf16 v[72:75], v[136:139], v[200:203], v[72:75]
	v_mfma_f32_16x16x32_bf16 v[132:135], v[128:131], v[164:167], v[132:135]
	v_mfma_f32_16x16x32_bf16 v[124:127], v[140:143], v[164:167], v[124:127]
	v_mfma_f32_16x16x32_bf16 v[108:111], v[128:131], v[188:191], v[108:111]
	v_mfma_f32_16x16x32_bf16 v[104:107], v[140:143], v[188:191], v[104:107]
	v_mfma_f32_16x16x32_bf16 v[92:95], v[128:131], v[196:199], v[92:95]
	v_mfma_f32_16x16x32_bf16 v[88:91], v[140:143], v[196:199], v[88:91]
	v_mfma_f32_16x16x32_bf16 v[76:79], v[128:131], v[216:219], v[76:79]
	v_mfma_f32_16x16x32_bf16 v[72:75], v[140:143], v[216:219], v[72:75]
	s_setprio 0
	s_setprio 1
	v_mfma_f32_16x16x32_bf16 v[116:119], v[144:147], v[160:163], v[116:119]
	v_mfma_f32_16x16x32_bf16 v[112:115], v[152:155], v[160:163], v[112:115]
	v_mfma_f32_16x16x32_bf16 v[100:103], v[144:147], v[184:187], v[100:103]
	v_mfma_f32_16x16x32_bf16 v[96:99], v[152:155], v[184:187], v[96:99]
	v_mfma_f32_16x16x32_bf16 v[84:87], v[144:147], v[192:195], v[84:87]
	v_mfma_f32_16x16x32_bf16 v[80:83], v[152:155], v[192:195], v[80:83]
	v_mfma_f32_16x16x32_bf16 v[68:71], v[144:147], v[200:203], v[68:71]
	v_mfma_f32_16x16x32_bf16 v[64:67], v[152:155], v[200:203], v[64:67]
	v_mfma_f32_16x16x32_bf16 v[116:119], v[148:151], v[164:167], v[116:119]
	v_mfma_f32_16x16x32_bf16 v[112:115], v[156:159], v[164:167], v[112:115]
	v_mfma_f32_16x16x32_bf16 v[100:103], v[148:151], v[188:191], v[100:103]
	v_mfma_f32_16x16x32_bf16 v[96:99], v[156:159], v[188:191], v[96:99]
	v_mfma_f32_16x16x32_bf16 v[84:87], v[148:151], v[196:199], v[84:87]
	v_mfma_f32_16x16x32_bf16 v[80:83], v[156:159], v[196:199], v[80:83]
	v_mfma_f32_16x16x32_bf16 v[68:71], v[148:151], v[216:219], v[68:71]
	v_mfma_f32_16x16x32_bf16 v[64:67], v[156:159], v[216:219], v[64:67]
	s_setprio 0
	s_barrier
	s_add_i32 s22, s41, s28
	v_lshl_add_u64 v[220:221], s[24:25], 0, v[170:171]
	s_mov_b32 m0, s22
	ds_read_b128 v[160:163], v211 offset:16384
	ds_read_b128 v[164:167], v211 offset:17408
	ds_read_b128 v[184:187], v211 offset:18432
	ds_read_b128 v[188:191], v211 offset:19456
	ds_read_b128 v[192:195], v211 offset:20480
	ds_read_b128 v[196:199], v211 offset:21504
	ds_read_b128 v[200:203], v211 offset:22528
	ds_read_b128 v[216:219], v211 offset:23552
	global_load_lds_dwordx4 v[220:221], off
	s_add_i32 m0, s22, 0x2000
	s_add_u32 s22, s24, 0xb0000
	v_lshl_add_u64 v[222:223], s[24:25], 0, v[174:175]
	s_addc_u32 s23, s25, 0
	s_add_i32 s48, s42, s28
	global_load_lds_dwordx4 v[222:223], off
	s_mov_b32 m0, s48
	v_lshl_add_u64 v[226:227], s[26:27], 0, v[172:173]
	global_load_lds_dwordx4 v170, s[22:23]
	s_add_i32 m0, s48, 0x2000
	s_nop 0
	global_load_lds_dwordx4 v174, s[22:23]
	v_lshl_add_u64 v[224:225], s[26:27], 0, v[168:169]
	s_mov_b32 m0, s29
	s_nop 0
	global_load_lds_dwordx4 v[224:225], off
	s_mov_b32 m0, s30
	s_nop 0
	global_load_lds_dwordx4 v[226:227], off
	s_waitcnt vmcnt(8)
	s_waitcnt lgkmcnt(0)
	s_nop 0
	s_barrier
	s_setprio 1
	s_waitcnt lgkmcnt(0)
	v_mfma_f32_16x16x32_bf16 v[60:63], v[120:123], v[160:163], v[60:63]
	v_mfma_f32_16x16x32_bf16 v[56:59], v[136:139], v[160:163], v[56:59]
	v_mfma_f32_16x16x32_bf16 v[44:47], v[120:123], v[184:187], v[44:47]
	v_mfma_f32_16x16x32_bf16 v[40:43], v[136:139], v[184:187], v[40:43]
	v_mfma_f32_16x16x32_bf16 v[28:31], v[120:123], v[192:195], v[28:31]
	v_mfma_f32_16x16x32_bf16 v[24:27], v[136:139], v[192:195], v[24:27]
	v_mfma_f32_16x16x32_bf16 v[12:15], v[120:123], v[200:203], v[12:15]
	v_mfma_f32_16x16x32_bf16 v[8:11], v[136:139], v[200:203], v[8:11]
	v_mfma_f32_16x16x32_bf16 v[60:63], v[128:131], v[164:167], v[60:63]
	v_mfma_f32_16x16x32_bf16 v[56:59], v[140:143], v[164:167], v[56:59]
	v_mfma_f32_16x16x32_bf16 v[44:47], v[128:131], v[188:191], v[44:47]
	v_mfma_f32_16x16x32_bf16 v[40:43], v[140:143], v[188:191], v[40:43]
	v_mfma_f32_16x16x32_bf16 v[28:31], v[128:131], v[196:199], v[28:31]
	v_mfma_f32_16x16x32_bf16 v[24:27], v[140:143], v[196:199], v[24:27]
	v_mfma_f32_16x16x32_bf16 v[12:15], v[128:131], v[216:219], v[12:15]
	v_mfma_f32_16x16x32_bf16 v[8:11], v[140:143], v[216:219], v[8:11]
	s_setprio 0
	s_setprio 1
	v_mfma_f32_16x16x32_bf16 v[52:55], v[144:147], v[160:163], v[52:55]
	v_mfma_f32_16x16x32_bf16 v[48:51], v[152:155], v[160:163], v[48:51]
	v_mfma_f32_16x16x32_bf16 v[36:39], v[144:147], v[184:187], v[36:39]
	v_mfma_f32_16x16x32_bf16 v[32:35], v[152:155], v[184:187], v[32:35]
	v_mfma_f32_16x16x32_bf16 v[20:23], v[144:147], v[192:195], v[20:23]
	v_mfma_f32_16x16x32_bf16 v[16:19], v[152:155], v[192:195], v[16:19]
	v_mfma_f32_16x16x32_bf16 v[4:7], v[144:147], v[200:203], v[4:7]
	v_mfma_f32_16x16x32_bf16 v[0:3], v[152:155], v[200:203], v[0:3]
	v_mfma_f32_16x16x32_bf16 v[52:55], v[148:151], v[164:167], v[52:55]
	v_mfma_f32_16x16x32_bf16 v[48:51], v[156:159], v[164:167], v[48:51]
	v_mfma_f32_16x16x32_bf16 v[36:39], v[148:151], v[188:191], v[36:39]
	v_mfma_f32_16x16x32_bf16 v[32:35], v[156:159], v[188:191], v[32:35]
	v_mfma_f32_16x16x32_bf16 v[20:23], v[148:151], v[196:199], v[20:23]
	v_mfma_f32_16x16x32_bf16 v[16:19], v[156:159], v[196:199], v[16:19]
	v_mfma_f32_16x16x32_bf16 v[4:7], v[148:151], v[216:219], v[4:7]
	v_mfma_f32_16x16x32_bf16 v[0:3], v[156:159], v[216:219], v[0:3]
	s_setprio 0
	s_barrier
	s_add_i32 s48, 0, 0x18000
	s_add_i32 s49, 0, 0x1c000
	v_add_u32_e32 v140, s48, v205
	v_add_u32_e32 v156, s49, v205
	ds_read_b128 v[120:123], v140
	ds_read_b128 v[128:131], v140 offset:1024
	ds_read_b128 v[136:139], v140 offset:2048
	ds_read_b128 v[140:143], v140 offset:3072
	ds_read_b128 v[144:147], v156
	ds_read_b128 v[148:151], v156 offset:1024
	ds_read_b128 v[152:155], v156 offset:2048
	ds_read_b128 v[156:159], v156 offset:3072
	s_add_u32 s22, s26, 0xb0000
	s_addc_u32 s23, s27, 0
	s_mov_b32 m0, s31
	ds_read_b128 v[160:163], v211 offset:32768
	ds_read_b128 v[164:167], v211 offset:33792
	ds_read_b128 v[184:187], v211 offset:34816
	ds_read_b128 v[188:191], v211 offset:35840
	ds_read_b128 v[192:195], v211 offset:36864
	ds_read_b128 v[196:199], v211 offset:37888
	ds_read_b128 v[200:203], v211 offset:38912
	ds_read_b128 v[216:219], v211 offset:39936
	global_load_lds_dwordx4 v168, s[22:23]
	s_mov_b32 m0, s33
	s_nop 0
	global_load_lds_dwordx4 v172, s[22:23]
	s_waitcnt vmcnt(8)
	s_waitcnt lgkmcnt(0)
	s_nop 0
	s_barrier
	s_setprio 1
	s_waitcnt lgkmcnt(0)
	v_mfma_f32_16x16x32_bf16 v[132:135], v[120:123], v[160:163], v[132:135]
	v_mfma_f32_16x16x32_bf16 v[124:127], v[136:139], v[160:163], v[124:127]
	v_mfma_f32_16x16x32_bf16 v[108:111], v[120:123], v[184:187], v[108:111]
	v_mfma_f32_16x16x32_bf16 v[104:107], v[136:139], v[184:187], v[104:107]
	v_mfma_f32_16x16x32_bf16 v[92:95], v[120:123], v[192:195], v[92:95]
	v_mfma_f32_16x16x32_bf16 v[88:91], v[136:139], v[192:195], v[88:91]
	v_mfma_f32_16x16x32_bf16 v[76:79], v[120:123], v[200:203], v[76:79]
	v_mfma_f32_16x16x32_bf16 v[72:75], v[136:139], v[200:203], v[72:75]
	v_mfma_f32_16x16x32_bf16 v[132:135], v[128:131], v[164:167], v[132:135]
	v_mfma_f32_16x16x32_bf16 v[124:127], v[140:143], v[164:167], v[124:127]
	v_mfma_f32_16x16x32_bf16 v[108:111], v[128:131], v[188:191], v[108:111]
	v_mfma_f32_16x16x32_bf16 v[104:107], v[140:143], v[188:191], v[104:107]
	v_mfma_f32_16x16x32_bf16 v[92:95], v[128:131], v[196:199], v[92:95]
	v_mfma_f32_16x16x32_bf16 v[88:91], v[140:143], v[196:199], v[88:91]
	v_mfma_f32_16x16x32_bf16 v[76:79], v[128:131], v[216:219], v[76:79]
	v_mfma_f32_16x16x32_bf16 v[72:75], v[140:143], v[216:219], v[72:75]
	s_setprio 0
	s_setprio 1
	v_mfma_f32_16x16x32_bf16 v[116:119], v[144:147], v[160:163], v[116:119]
	v_mfma_f32_16x16x32_bf16 v[112:115], v[152:155], v[160:163], v[112:115]
	v_mfma_f32_16x16x32_bf16 v[100:103], v[144:147], v[184:187], v[100:103]
	v_mfma_f32_16x16x32_bf16 v[96:99], v[152:155], v[184:187], v[96:99]
	v_mfma_f32_16x16x32_bf16 v[84:87], v[144:147], v[192:195], v[84:87]
	v_mfma_f32_16x16x32_bf16 v[80:83], v[152:155], v[192:195], v[80:83]
	v_mfma_f32_16x16x32_bf16 v[68:71], v[144:147], v[200:203], v[68:71]
	v_mfma_f32_16x16x32_bf16 v[64:67], v[152:155], v[200:203], v[64:67]
	v_mfma_f32_16x16x32_bf16 v[116:119], v[148:151], v[164:167], v[116:119]
	v_mfma_f32_16x16x32_bf16 v[112:115], v[156:159], v[164:167], v[112:115]
	v_mfma_f32_16x16x32_bf16 v[100:103], v[148:151], v[188:191], v[100:103]
	v_mfma_f32_16x16x32_bf16 v[96:99], v[156:159], v[188:191], v[96:99]
	v_mfma_f32_16x16x32_bf16 v[84:87], v[148:151], v[196:199], v[84:87]
	v_mfma_f32_16x16x32_bf16 v[80:83], v[156:159], v[196:199], v[80:83]
	v_mfma_f32_16x16x32_bf16 v[68:71], v[148:151], v[216:219], v[68:71]
	v_mfma_f32_16x16x32_bf16 v[64:67], v[156:159], v[216:219], v[64:67]
	s_setprio 0
	s_barrier
	s_add_i32 s22, s48, s28
	v_lshl_add_u64 v[220:221], v[220:221], 0, s[8:9]
	s_mov_b32 m0, s22
	ds_read_b128 v[160:163], v211 offset:49152
	ds_read_b128 v[164:167], v211 offset:50176
	ds_read_b128 v[184:187], v211 offset:51200
	ds_read_b128 v[188:191], v211 offset:52224
	ds_read_b128 v[192:195], v211 offset:53248
	ds_read_b128 v[196:199], v211 offset:54272
	ds_read_b128 v[200:203], v211 offset:55296
	ds_read_b128 v[216:219], v211 offset:56320
	global_load_lds_dwordx4 v[220:221], off
	s_add_i32 m0, s22, 0x2000
	s_add_u32 s22, s24, 0xb0080
	v_lshl_add_u64 v[220:221], v[222:223], 0, s[8:9]
	s_addc_u32 s23, s25, 0
	s_add_i32 s24, s49, s28
	global_load_lds_dwordx4 v[220:221], off
	s_mov_b32 m0, s24
	s_nop 0
	global_load_lds_dwordx4 v170, s[22:23]
	s_add_i32 m0, s24, 0x2000
	s_nop 0
	global_load_lds_dwordx4 v174, s[22:23]
	v_lshl_add_u64 v[220:221], v[224:225], 0, s[8:9]
	s_mov_b32 m0, s37
	s_nop 0
	global_load_lds_dwordx4 v[220:221], off
	v_lshl_add_u64 v[220:221], v[226:227], 0, s[8:9]
	s_mov_b32 m0, s38
	s_nop 0
	global_load_lds_dwordx4 v[220:221], off
	s_waitcnt vmcnt(8)
	s_waitcnt lgkmcnt(0)
	s_barrier
	s_setprio 1
	s_waitcnt lgkmcnt(0)
	v_mfma_f32_16x16x32_bf16 v[60:63], v[120:123], v[160:163], v[60:63]
	v_mfma_f32_16x16x32_bf16 v[56:59], v[136:139], v[160:163], v[56:59]
	v_mfma_f32_16x16x32_bf16 v[44:47], v[120:123], v[184:187], v[44:47]
	v_mfma_f32_16x16x32_bf16 v[40:43], v[136:139], v[184:187], v[40:43]
	v_mfma_f32_16x16x32_bf16 v[28:31], v[120:123], v[192:195], v[28:31]
	v_mfma_f32_16x16x32_bf16 v[24:27], v[136:139], v[192:195], v[24:27]
	v_mfma_f32_16x16x32_bf16 v[12:15], v[120:123], v[200:203], v[12:15]
	v_mfma_f32_16x16x32_bf16 v[8:11], v[136:139], v[200:203], v[8:11]
	v_mfma_f32_16x16x32_bf16 v[60:63], v[128:131], v[164:167], v[60:63]
	v_mfma_f32_16x16x32_bf16 v[56:59], v[140:143], v[164:167], v[56:59]
	v_mfma_f32_16x16x32_bf16 v[44:47], v[128:131], v[188:191], v[44:47]
	v_mfma_f32_16x16x32_bf16 v[40:43], v[140:143], v[188:191], v[40:43]
	v_mfma_f32_16x16x32_bf16 v[28:31], v[128:131], v[196:199], v[28:31]
	v_mfma_f32_16x16x32_bf16 v[24:27], v[140:143], v[196:199], v[24:27]
	v_mfma_f32_16x16x32_bf16 v[12:15], v[128:131], v[216:219], v[12:15]
	v_mfma_f32_16x16x32_bf16 v[8:11], v[140:143], v[216:219], v[8:11]
	s_setprio 0
	s_setprio 1
	v_mfma_f32_16x16x32_bf16 v[52:55], v[144:147], v[160:163], v[52:55]
	v_mfma_f32_16x16x32_bf16 v[48:51], v[152:155], v[160:163], v[48:51]
	v_mfma_f32_16x16x32_bf16 v[36:39], v[144:147], v[184:187], v[36:39]
	v_mfma_f32_16x16x32_bf16 v[32:35], v[152:155], v[184:187], v[32:35]
	v_mfma_f32_16x16x32_bf16 v[20:23], v[144:147], v[192:195], v[20:23]
	v_mfma_f32_16x16x32_bf16 v[16:19], v[152:155], v[192:195], v[16:19]
	v_mfma_f32_16x16x32_bf16 v[4:7], v[144:147], v[200:203], v[4:7]
	v_mfma_f32_16x16x32_bf16 v[0:3], v[152:155], v[200:203], v[0:3]
	v_mfma_f32_16x16x32_bf16 v[52:55], v[148:151], v[164:167], v[52:55]
	v_mfma_f32_16x16x32_bf16 v[48:51], v[156:159], v[164:167], v[48:51]
	v_mfma_f32_16x16x32_bf16 v[36:39], v[148:151], v[188:191], v[36:39]
	v_mfma_f32_16x16x32_bf16 v[32:35], v[156:159], v[188:191], v[32:35]
	v_mfma_f32_16x16x32_bf16 v[20:23], v[148:151], v[196:199], v[20:23]
	v_mfma_f32_16x16x32_bf16 v[16:19], v[156:159], v[196:199], v[16:19]
	v_mfma_f32_16x16x32_bf16 v[4:7], v[148:151], v[216:219], v[4:7]
	v_mfma_f32_16x16x32_bf16 v[0:3], v[156:159], v[216:219], v[0:3]
	s_setprio 0
	s_barrier
	s_add_i32 s47, s47, 2
	s_add_u32 s21, s21, 0x100
	s_addc_u32 s46, s46, 0
	s_cmp_gt_u32 s47, 41
	s_mov_b64 s[22:23], s[4:5]
	s_cbranch_scc0 .LBB0_1325
	s_and_b64 vcc, exec, s[10:11]
	s_cbranch_vccz .LBB0_1328
	s_barrier
